# lazy softmax rescale check on the tile row-sum (drops 32-value max tree); indexer scoring loop rewritten: software-pipelined MFMA chains, one permlane swap per value pair, 2-op sortable-key transform,
# speedup vs baseline: 1.0143x; 1.0143x over previous
; __device__ __forceinline__ float swap32_max(float v) { auto rr = __builtin_amdgcn_permlane32_swap(__float_as_uint(v), __float_as_uint(v), false, false); return fmaxf(__uint_as_float(rr[0]), __uint_as_float(rr[1])); }
; template <int D, int DV, bool TAB, bool BITS, int KT> ...
;     ...
;             mx = swap32_max(mx);
;             if (__any(mx > 8.0f)) {
;                 const float dl = fmaxf(mx, 0.f); mhat += dl;
; #pragma unroll
;                 for (int r = 0; r < 16; ++r) { p0[r] -= dl; p1[r] -= dl; }
;                 const float alpha = __builtin_amdgcn_exp2f(-dl); l_run *= alpha;
;                 if (hi == 0) wsf[r32] = alpha;
;                 __builtin_amdgcn_fence(__ATOMIC_RELEASE, "wavefront"); __builtin_amdgcn_wave_barrier();
; #pragma unroll
;                 for (int j = 0; j < 4; ++j) { const f32x4 a4 = *(const f32x4*)(wsf + 8 * j + 4 * hi);
; #pragma unroll
;                     for (int dt = 0; dt < DV / 32; ++dt) { o[dt][4 * j + 0] *= a4[0]; o[dt][4 * j + 1] *= a4[1]; o[dt][4 * j + 2] *= a4[2]; o[dt][4 * j + 3] *= a4[3]; } }
;                 __builtin_amdgcn_fence(__ATOMIC_RELEASE, "wavefront"); __builtin_amdgcn_wave_barrier();
;             }
.Lrare_0:
	s_nop 11
	v_mov_b32_e32 v184, v66
	s_nop 1
	v_permlane32_swap_b32_e32 v66, v184
	v_add_f32_e32 v158, v66, v184
	v_log_f32_e32 v158, v158
	s_nop 0
	v_max_f32_e32 v158, v158, v158
	v_max_f32_e32 v158, 0, v158
	v_exp_f32_e64 v184, -v158
	s_and_saveexec_b64 s[74:75], s[6:7]
	ds_write_b32 v162, v184
	s_or_b64 exec, exec, s[74:75]
	ds_read_b128 v[192:195], v177
	ds_read_b128 v[196:199], v177 offset:32
	ds_read_b128 v[200:203], v177 offset:64
	ds_read_b128 v[204:207], v177 offset:96
	v_add_f32_e32 v181, v181, v158
	s_mov_b32 s100, 1
	v_mul_f32_e32 v179, v179, v184
	s_waitcnt lgkmcnt(0)
	v_pk_mul_f32 v[64:65], v[64:65], v[206:207]
	v_pk_mul_f32 v[60:61], v[60:61], v[202:203]
	v_pk_mul_f32 v[56:57], v[56:57], v[198:199]
	v_pk_mul_f32 v[52:53], v[52:53], v[194:195]
	v_pk_mul_f32 v[62:63], v[62:63], v[204:205]
	v_pk_mul_f32 v[58:59], v[58:59], v[200:201]
	v_pk_mul_f32 v[54:55], v[54:55], v[196:197]
	v_pk_mul_f32 v[50:51], v[50:51], v[192:193]
	v_pk_mul_f32 v[48:49], v[48:49], v[206:207]
	v_pk_mul_f32 v[44:45], v[44:45], v[202:203]
	v_pk_mul_f32 v[40:41], v[40:41], v[198:199]
	v_pk_mul_f32 v[36:37], v[36:37], v[194:195]
	v_pk_mul_f32 v[46:47], v[46:47], v[204:205]
	v_pk_mul_f32 v[42:43], v[42:43], v[200:201]
	v_pk_mul_f32 v[38:39], v[38:39], v[196:197]
	v_pk_mul_f32 v[34:35], v[34:35], v[192:193]
	v_pk_mul_f32 v[32:33], v[32:33], v[206:207]
	v_pk_mul_f32 v[28:29], v[28:29], v[202:203]
	v_pk_mul_f32 v[24:25], v[24:25], v[198:199]
	v_pk_mul_f32 v[20:21], v[20:21], v[194:195]
	v_pk_mul_f32 v[30:31], v[30:31], v[204:205]
	v_pk_mul_f32 v[26:27], v[26:27], v[200:201]
	v_pk_mul_f32 v[22:23], v[22:23], v[196:197]
	v_pk_mul_f32 v[18:19], v[18:19], v[192:193]
	v_pk_mul_f32 v[16:17], v[16:17], v[206:207]
	v_pk_mul_f32 v[12:13], v[12:13], v[202:203]
	v_pk_mul_f32 v[8:9], v[8:9], v[198:199]
	v_pk_mul_f32 v[4:5], v[4:5], v[194:195]
	v_pk_mul_f32 v[14:15], v[14:15], v[204:205]
	v_pk_mul_f32 v[10:11], v[10:11], v[200:201]
	v_pk_mul_f32 v[6:7], v[6:7], v[196:197]
	v_pk_mul_f32 v[2:3], v[2:3], v[192:193]
	s_branch .Lback_0
.Lrare_1:
	s_nop 11
	v_mov_b32_e32 v183, v66
	s_nop 1
	v_permlane32_swap_b32_e32 v66, v183
	v_add_f32_e32 v158, v66, v183
	v_log_f32_e32 v158, v158
	s_nop 0
	v_max_f32_e32 v158, v158, v158
	v_max_f32_e32 v158, 0, v158
	v_exp_f32_e64 v183, -v158
	s_and_saveexec_b64 s[74:75], s[6:7]
	ds_write_b32 v162, v183
	s_or_b64 exec, exec, s[74:75]
	ds_read_b128 v[192:195], v177
	ds_read_b128 v[196:199], v177 offset:32
	ds_read_b128 v[200:203], v177 offset:64
	ds_read_b128 v[204:207], v177 offset:96
	v_add_f32_e32 v181, v181, v158
	s_mov_b32 s100, 1
	v_mul_f32_e32 v179, v179, v183
	s_waitcnt lgkmcnt(0)
	v_pk_mul_f32 v[64:65], v[64:65], v[206:207]
	v_pk_mul_f32 v[60:61], v[60:61], v[202:203]
	v_pk_mul_f32 v[56:57], v[56:57], v[198:199]
	v_pk_mul_f32 v[52:53], v[52:53], v[194:195]
	v_pk_mul_f32 v[62:63], v[62:63], v[204:205]
	v_pk_mul_f32 v[58:59], v[58:59], v[200:201]
	v_pk_mul_f32 v[54:55], v[54:55], v[196:197]
	v_pk_mul_f32 v[50:51], v[50:51], v[192:193]
	v_pk_mul_f32 v[48:49], v[48:49], v[206:207]
	v_pk_mul_f32 v[44:45], v[44:45], v[202:203]
	v_pk_mul_f32 v[40:41], v[40:41], v[198:199]
	v_pk_mul_f32 v[36:37], v[36:37], v[194:195]
	v_pk_mul_f32 v[46:47], v[46:47], v[204:205]
	v_pk_mul_f32 v[42:43], v[42:43], v[200:201]
	v_pk_mul_f32 v[38:39], v[38:39], v[196:197]
	v_pk_mul_f32 v[34:35], v[34:35], v[192:193]
	v_pk_mul_f32 v[32:33], v[32:33], v[206:207]
	v_pk_mul_f32 v[28:29], v[28:29], v[202:203]
	v_pk_mul_f32 v[24:25], v[24:25], v[198:199]
	v_pk_mul_f32 v[20:21], v[20:21], v[194:195]
	v_pk_mul_f32 v[30:31], v[30:31], v[204:205]
	v_pk_mul_f32 v[26:27], v[26:27], v[200:201]
	v_pk_mul_f32 v[22:23], v[22:23], v[196:197]
	v_pk_mul_f32 v[18:19], v[18:19], v[192:193]
	v_pk_mul_f32 v[16:17], v[16:17], v[206:207]
	v_pk_mul_f32 v[12:13], v[12:13], v[202:203]
	v_pk_mul_f32 v[8:9], v[8:9], v[198:199]
	v_pk_mul_f32 v[4:5], v[4:5], v[194:195]
	v_pk_mul_f32 v[14:15], v[14:15], v[204:205]
	v_pk_mul_f32 v[10:11], v[10:11], v[200:201]
	v_pk_mul_f32 v[6:7], v[6:7], v[196:197]
	v_pk_mul_f32 v[2:3], v[2:3], v[192:193]
	s_branch .Lback_1

; __device__ __forceinline__ int crowc(int r) { return (r & 3) + 8 * (r >> 2); }
; template <int D, int DV, bool TAB, bool BITS, int KT> ...
;     ...
;             if (D == 64) {
;                 bf16x8 ka[4], kb[4];
;                 if (TAB) {
; #pragma unroll
;                     for (int r = 0; r < 16; ++r) p0[r] = tabL[tj + crowc(r)]; }
; #pragma unroll
;                 for (int kk = 0; kk < 4; ++kk) ka[kk] = *(const bf16x8*)(Kl + r32 * KP + (kk * 16 + 8 * hi) * 2);
;                 if (TAB) {
; #pragma unroll
;                     for (int r = 0; r < 16; ++r) p1[r] = tabL[tj + 32 + crowc(r)]; }
; #pragma unroll
;                 for (int kk = 0; kk < 4; ++kk) kb[kk] = *(const bf16x8*)(Kl + (32 + r32) * KP + (kk * 16 + 8 * hi) * 2);
;                 __builtin_amdgcn_sched_barrier(0);
; #pragma unroll
;                 for (int r = 0; r < 16; ++r) { if (TAB) p0[r] -= mhat; else p0[r] = nm; if (BITS) { if (!((w0 >> crowc(r)) & 1u)) p0[r] = NEGV; } }
;                 __builtin_amdgcn_sched_barrier(0);
; #pragma unroll
;                 for (int kk = 0; kk < 4; ++kk) p0 = __builtin_amdgcn_mfma_f32_32x32x16_bf16(ka[kk], qf[kk], p0, 0, 0, 0);
; #pragma unroll
;                 for (int r = 0; r < 16; ++r) { if (TAB) p1[r] -= mhat; else p1[r] = nm; if (BITS) { if (!((w1 >> crowc(r)) & 1u)) p1[r] = NEGV; } }
;                 __builtin_amdgcn_sched_barrier(0);
; #pragma unroll
;                 for (int kk = 0; kk < 4; ++kk) p1 = __builtin_amdgcn_mfma_f32_32x32x16_bf16(kb[kk], qf[kk], p1, 0, 0, 0);
;     ...
;             float rs = 0.f;
;             bf16x8 vc[DV / 32];
;     ...
; #pragma unroll
;             for (int g = 0; g < 4; ++g) {
;                 AT_VLOAD(vc, g);
;                 float e[8];
; #pragma unroll
;                 for (int i = 0; i < 8; ++i) { e[i] = __builtin_amdgcn_exp2f(g < 2 ? p0[(g & 1) * 8 + i] : p1[(g & 1) * 8 + i]); rs += e[i]; }
;                 u32x4v pw; pw.x = cvtpk(e[0], e[1]); pw.y = cvtpk(e[2], e[3]); pw.z = cvtpk(e[4], e[5]); pw.w = cvtpk(e[6], e[7]);
;                 const bf16x8 pa = __builtin_bit_cast(bf16x8, pw);
;                 __builtin_amdgcn_sched_barrier(0);
; #pragma unroll
;                 for (int dt = 0; dt < DV / 32; ++dt) o[dt] = __builtin_amdgcn_mfma_f32_32x32x16_bf16(pa, vc[dt], o[dt], 0, 0, 0);
;                 __builtin_amdgcn_sched_barrier(0x1 | 0x2 | 0x100);
;             }
;             l_run += rs;
.LBB0_350:
	v_exp_f32_e32 v82, v82
	v_exp_f32_e32 v83, v83
	v_exp_f32_e32 v84, v84
	v_exp_f32_e32 v85, v85
	v_add_u32_e32 v158, v182, v178
	v_add_f32_e32 v188, 0, v82
	v_exp_f32_e32 v86, v86
	v_add_u32_e32 v184, 0x9000, v158
	v_add_u32_e32 v185, 0xb000, v158
	v_add_u32_e32 v187, 0xd000, v158
	v_add_u32_e32 v158, 0xf000, v158
	v_add_f32_e32 v188, v83, v188
	v_exp_f32_e32 v87, v87
	ds_read2_b64 v[192:195], v184 offset1:2
	ds_read2_b64 v[196:199], v185 offset0:32 offset1:34
	ds_read2_b64 v[200:203], v187 offset0:64 offset1:66
	ds_read2_b64 v[204:207], v158 offset0:96 offset1:98
	v_add_f32_e32 v188, v84, v188
	v_exp_f32_e32 v88, v88
	v_exp_f32_e32 v89, v89
	v_add_f32_e32 v188, v85, v188
	v_add_f32_e32 v188, v86, v188
	v_add_f32_e32 v188, v87, v188
	v_add_f32_e32 v188, v88, v188
	v_cvt_pk_bf16_f32 v82, v82, v83
	v_cvt_pk_bf16_f32 v83, v84, v85
	v_cvt_pk_bf16_f32 v84, v86, v87
	v_cvt_pk_bf16_f32 v85, v88, v89
	v_exp_f32_e32 v90, v90
	v_exp_f32_e32 v91, v91
	s_waitcnt lgkmcnt(3)
	v_mfma_f32_32x32x16_bf16 v[50:65], v[82:85], v[192:195], v[50:65]
	v_exp_f32_e32 v92, v92
	v_add_f32_e32 v188, v89, v188
	v_exp_f32_e32 v93, v93
	v_add_f32_e32 v188, v90, v188
	v_exp_f32_e32 v94, v94
	v_add_f32_e32 v188, v91, v188
	v_exp_f32_e32 v95, v95
	s_waitcnt lgkmcnt(2)
	v_mfma_f32_32x32x16_bf16 v[34:49], v[82:85], v[196:199], v[34:49]
	v_add_f32_e32 v188, v92, v188
	v_exp_f32_e32 v96, v96
	v_exp_f32_e32 v97, v97
	v_add_f32_e32 v188, v93, v188
	v_add_f32_e32 v188, v94, v188
	v_add_f32_e32 v188, v95, v188
	v_add_f32_e32 v188, v96, v188
	s_waitcnt lgkmcnt(1)
	v_mfma_f32_32x32x16_bf16 v[18:33], v[82:85], v[200:203], v[18:33]
	v_cvt_pk_bf16_f32 v90, v90, v91
	v_cvt_pk_bf16_f32 v91, v92, v93
	v_cvt_pk_bf16_f32 v92, v94, v95
	v_cvt_pk_bf16_f32 v93, v96, v97
	s_waitcnt lgkmcnt(0)
	v_mfma_f32_32x32x16_bf16 v[2:17], v[82:85], v[204:207], v[2:17]
	ds_read2_b64 v[82:85], v184 offset0:4 offset1:6
	ds_read2_b64 v[86:89], v185 offset0:36 offset1:38
	ds_read2_b64 v[192:195], v187 offset0:68 offset1:70
	ds_read2_b64 v[196:199], v158 offset0:100 offset1:102
	v_exp_f32_e32 v66, v66
	v_exp_f32_e32 v67, v67
	s_waitcnt lgkmcnt(3)
	v_mfma_f32_32x32x16_bf16 v[50:65], v[90:93], v[82:85], v[50:65]
	v_exp_f32_e32 v68, v68
	v_add_f32_e32 v188, v97, v188
	v_exp_f32_e32 v69, v69
	v_add_f32_e32 v188, v66, v188
	v_exp_f32_e32 v70, v70
	v_add_f32_e32 v188, v67, v188
	v_exp_f32_e32 v71, v71
	s_waitcnt lgkmcnt(2)
	v_mfma_f32_32x32x16_bf16 v[34:49], v[90:93], v[86:89], v[34:49]
	v_add_f32_e32 v188, v68, v188
	v_exp_f32_e32 v72, v72
	v_exp_f32_e32 v73, v73
	v_add_f32_e32 v188, v69, v188
	v_add_f32_e32 v188, v70, v188
	v_add_f32_e32 v188, v71, v188
	v_add_f32_e32 v188, v72, v188
	s_waitcnt lgkmcnt(1)
	v_mfma_f32_32x32x16_bf16 v[18:33], v[90:93], v[192:195], v[18:33]
	v_cvt_pk_bf16_f32 v66, v66, v67
	v_cvt_pk_bf16_f32 v67, v68, v69
	v_cvt_pk_bf16_f32 v68, v70, v71
	v_cvt_pk_bf16_f32 v69, v72, v73
	s_waitcnt lgkmcnt(0)
	v_mfma_f32_32x32x16_bf16 v[2:17], v[90:93], v[196:199], v[2:17]
	ds_read2_b64 v[82:85], v184 offset0:8 offset1:10
	ds_read2_b64 v[86:89], v185 offset0:40 offset1:42
	ds_read2_b64 v[90:93], v187 offset0:72 offset1:74
	ds_read2_b64 v[94:97], v158 offset0:104 offset1:106
	v_exp_f32_e32 v74, v74
	v_exp_f32_e32 v75, v75
	s_waitcnt lgkmcnt(3)
	v_mfma_f32_32x32x16_bf16 v[50:65], v[66:69], v[82:85], v[50:65]
	v_exp_f32_e32 v76, v76
	v_exp_f32_e32 v77, v77
	v_exp_f32_e32 v78, v78
	v_exp_f32_e32 v79, v79
	v_exp_f32_e32 v80, v80
	v_exp_f32_e32 v81, v81
	s_waitcnt lgkmcnt(2)
	v_mfma_f32_32x32x16_bf16 v[34:49], v[66:69], v[86:89], v[34:49]
	s_waitcnt lgkmcnt(1)
	v_mfma_f32_32x32x16_bf16 v[18:33], v[66:69], v[90:93], v[18:33]
	v_add_f32_e32 v90, v73, v188
	v_add_f32_e32 v90, v74, v90
	v_add_f32_e32 v90, v75, v90
	v_add_f32_e32 v90, v76, v90
	v_add_f32_e32 v90, v77, v90
	v_add_f32_e32 v90, v78, v90
	v_add_f32_e32 v90, v79, v90
	s_waitcnt lgkmcnt(0)
	v_mfma_f32_32x32x16_bf16 v[2:17], v[66:69], v[94:97], v[2:17]
	ds_read2_b64 v[66:69], v184 offset0:12 offset1:14
	ds_read2_b64 v[70:73], v185 offset0:44 offset1:46
	ds_read2_b64 v[82:85], v187 offset0:76 offset1:78
	ds_read2_b64 v[86:89], v158 offset0:108 offset1:110
	v_add_f32_e32 v90, v80, v90
	v_cvt_pk_bf16_f32 v74, v74, v75
	v_cvt_pk_bf16_f32 v75, v76, v77
	v_cvt_pk_bf16_f32 v76, v78, v79
	v_cvt_pk_bf16_f32 v77, v80, v81
	s_waitcnt lgkmcnt(3)
	s_nop 0
	v_mfma_f32_32x32x16_bf16 v[50:65], v[74:77], v[66:69], v[50:65]
	v_add_f32_e32 v66, v81, v90
	v_add_f32_e32 v179, v179, v66
	v_cmp_lt_f32_e32 vcc, 0x43800000, v66
	s_waitcnt lgkmcnt(2)
	v_mfma_f32_32x32x16_bf16 v[34:49], v[74:77], v[70:73], v[34:49]
	s_waitcnt lgkmcnt(1)
	v_mfma_f32_32x32x16_bf16 v[18:33], v[74:77], v[82:85], v[18:33]
	s_waitcnt lgkmcnt(0)
	v_mfma_f32_32x32x16_bf16 v[2:17], v[74:77], v[86:89], v[2:17]
	s_cbranch_vccnz .Lrare_0
.Lback_0:
.LBB0_351:
	s_sub_i32 s12, s64, 64
	s_cmp_le_i32 s12, s63
	s_cselect_b64 s[12:13], -1, 0
	s_add_i32 s50, s64, -1
	s_cmp_ge_i32 s50, s79
	s_cselect_b64 s[52:53], -1, 0
	s_and_b64 s[12:13], s[12:13], s[52:53]
	s_andn2_b64 vcc, exec, s[12:13]
	s_cbranch_vccnz .LBB0_357
	s_cmp_lg_u32 s100, 0
	s_cbranch_scc1 .Lslow_qk_a1s1
	ds_read_b128 v[66:69], v183 offset:9216
	ds_read_b128 v[70:73], v183 offset:9248
	ds_read2_b32 v[90:91], v180 offset0:80 offset1:81
	ds_read2_b32 v[92:93], v180 offset0:82 offset1:83
	ds_read2_b32 v[94:95], v180 offset0:88 offset1:89
	ds_read2_b32 v[96:97], v180 offset0:90 offset1:91
	ds_read2_b32 v[82:83], v180 offset0:64 offset1:65
	ds_read2_b32 v[84:85], v180 offset0:66 offset1:67
	ds_read2_b32 v[86:87], v180 offset0:72 offset1:73
	ds_read2_b32 v[88:89], v180 offset0:74 offset1:75
	ds_read_b128 v[208:211], v183 offset:9280
	ds_read_b128 v[212:215], v183 offset:9312
	s_waitcnt lgkmcnt(2)
	v_mfma_f32_32x32x16_bf16 v[82:97], v[66:69], v[134:137], v[82:97]
	v_mfma_f32_32x32x16_bf16 v[82:97], v[70:73], v[130:133], v[82:97]
	ds_read_b128 v[192:195], v183 offset:13824
	ds_read_b128 v[196:199], v183 offset:13856
	ds_read_b128 v[200:203], v183 offset:13888
	ds_read_b128 v[204:207], v183 offset:13920
	ds_read2_b32 v[66:67], v180 offset0:96 offset1:97
	ds_read2_b32 v[68:69], v180 offset0:98 offset1:99
	ds_read2_b32 v[70:71], v180 offset0:104 offset1:105
	ds_read2_b32 v[72:73], v180 offset0:106 offset1:107
	ds_read2_b32 v[74:75], v180 offset0:112 offset1:113
	ds_read2_b32 v[76:77], v180 offset0:114 offset1:115
	ds_read2_b32 v[78:79], v180 offset0:120 offset1:121
	ds_read2_b32 v[80:81], v180 offset0:122 offset1:123
	s_waitcnt lgkmcnt(12)
	v_mfma_f32_32x32x16_bf16 v[82:97], v[208:211], v[126:129], v[82:97]
	v_mfma_f32_32x32x16_bf16 v[82:97], v[212:215], v[122:125], v[82:97]
	s_waitcnt lgkmcnt(0)
	v_mfma_f32_32x32x16_bf16 v[66:81], v[192:195], v[134:137], v[66:81]
	v_mfma_f32_32x32x16_bf16 v[66:81], v[196:199], v[130:133], v[66:81]
	v_mfma_f32_32x32x16_bf16 v[66:81], v[200:203], v[126:129], v[66:81]
	v_mfma_f32_32x32x16_bf16 v[66:81], v[204:207], v[122:125], v[66:81]

; __device__ __forceinline__ unsigned cvtpk(float lo, float hi) { f32x2_t v = {lo, hi}; bf16x2_t b = __builtin_convertvector(v, bf16x2_t); return __builtin_bit_cast(unsigned, b); }
; #define AT_VLOAD(dst, g) do { _Pragma("unroll") for (int dt = 0; dt < DV / 32; ++dt) { const unsigned char* vp = Vl + (dt * 32 + r32) * VP + (16 * (g) + 4 * hi) * 2; \
;                 const s16x4 lo = *(const s16x4*)vp, hh = *(const s16x4*)(vp + 16); dst[dt] = (bf16x8){lo[0], lo[1], lo[2], lo[3], hh[0], hh[1], hh[2], hh[3]}; } } while (0)
; template <int D, int DV, bool TAB, bool BITS, int KT> ...
;     ...
;             float rs = 0.f;
;             bf16x8 vc[DV / 32];
;     ...
; #pragma unroll
;             for (int g = 0; g < 4; ++g) {
;                 AT_VLOAD(vc, g);
;                 float e[8];
; #pragma unroll
;                 for (int i = 0; i < 8; ++i) { e[i] = __builtin_amdgcn_exp2f(g < 2 ? p0[(g & 1) * 8 + i] : p1[(g & 1) * 8 + i]); rs += e[i]; }
;                 u32x4v pw; pw.x = cvtpk(e[0], e[1]); pw.y = cvtpk(e[2], e[3]); pw.z = cvtpk(e[4], e[5]); pw.w = cvtpk(e[6], e[7]);
;                 const bf16x8 pa = __builtin_bit_cast(bf16x8, pw);
;                 __builtin_amdgcn_sched_barrier(0);
; #pragma unroll
;                 for (int dt = 0; dt < DV / 32; ++dt) o[dt] = __builtin_amdgcn_mfma_f32_32x32x16_bf16(pa, vc[dt], o[dt], 0, 0, 0);
;                 __builtin_amdgcn_sched_barrier(0x1 | 0x2 | 0x100);
;             }
;             l_run += rs;
;     ...
;         }
;         }
;         if (t + 1 < t_hi) AT_STORE(cur ^ 1);
.LBB0_356:
	v_exp_f32_e32 v82, v82
	v_exp_f32_e32 v83, v83
	v_exp_f32_e32 v84, v84
	v_exp_f32_e32 v85, v85
	v_add_u32_e32 v158, v182, v178
	v_add_f32_e32 v190, 0, v82
	v_exp_f32_e32 v86, v86
	v_add_u32_e32 v187, 0x9000, v158
	v_add_u32_e32 v188, 0xb000, v158
	v_add_u32_e32 v189, 0xd000, v158
	v_add_u32_e32 v158, 0xf000, v158
	v_add_f32_e32 v190, v83, v190
	v_exp_f32_e32 v87, v87
	ds_read2_b64 v[182:185], v187 offset0:16 offset1:18
	ds_read2_b64 v[192:195], v188 offset0:48 offset1:50
	ds_read2_b64 v[196:199], v189 offset0:80 offset1:82
	ds_read2_b64 v[200:203], v158 offset0:112 offset1:114
	v_add_f32_e32 v190, v84, v190
	v_exp_f32_e32 v88, v88
	v_exp_f32_e32 v89, v89
	v_add_f32_e32 v190, v85, v190
	v_add_f32_e32 v190, v86, v190
	v_add_f32_e32 v190, v87, v190
	v_add_f32_e32 v190, v88, v190
	v_cvt_pk_bf16_f32 v82, v82, v83
	v_cvt_pk_bf16_f32 v83, v84, v85
	v_cvt_pk_bf16_f32 v84, v86, v87
	v_cvt_pk_bf16_f32 v85, v88, v89
	v_exp_f32_e32 v90, v90
	v_exp_f32_e32 v91, v91
	s_waitcnt lgkmcnt(3)
	v_mfma_f32_32x32x16_bf16 v[50:65], v[82:85], v[182:185], v[50:65]
	v_exp_f32_e32 v92, v92
	v_add_f32_e32 v190, v89, v190
	v_exp_f32_e32 v93, v93
	v_add_f32_e32 v190, v90, v190
	v_exp_f32_e32 v94, v94
	v_add_f32_e32 v190, v91, v190
	v_exp_f32_e32 v95, v95
	s_waitcnt lgkmcnt(2)
	v_mfma_f32_32x32x16_bf16 v[34:49], v[82:85], v[192:195], v[34:49]
	v_add_f32_e32 v190, v92, v190
	v_exp_f32_e32 v96, v96
	v_exp_f32_e32 v97, v97
	v_add_f32_e32 v190, v93, v190
	v_add_f32_e32 v190, v94, v190
	v_add_f32_e32 v190, v95, v190
	v_add_f32_e32 v190, v96, v190
	s_waitcnt lgkmcnt(1)
	v_mfma_f32_32x32x16_bf16 v[18:33], v[82:85], v[196:199], v[18:33]
	v_cvt_pk_bf16_f32 v90, v90, v91
	v_cvt_pk_bf16_f32 v91, v92, v93
	v_cvt_pk_bf16_f32 v92, v94, v95
	v_cvt_pk_bf16_f32 v93, v96, v97
	s_waitcnt lgkmcnt(0)
	v_mfma_f32_32x32x16_bf16 v[2:17], v[82:85], v[200:203], v[2:17]
	ds_read2_b64 v[82:85], v187 offset0:20 offset1:22
	ds_read2_b64 v[86:89], v188 offset0:52 offset1:54
	ds_read2_b64 v[182:185], v189 offset0:84 offset1:86
	ds_read2_b64 v[192:195], v158 offset0:116 offset1:118
	v_exp_f32_e32 v66, v66
	v_exp_f32_e32 v67, v67
	s_waitcnt lgkmcnt(3)
	v_mfma_f32_32x32x16_bf16 v[50:65], v[90:93], v[82:85], v[50:65]
	v_exp_f32_e32 v68, v68
	v_exp_f32_e32 v69, v69
	v_exp_f32_e32 v70, v70
	v_exp_f32_e32 v71, v71
	v_exp_f32_e32 v72, v72
	v_exp_f32_e32 v73, v73
	s_waitcnt lgkmcnt(2)
	v_mfma_f32_32x32x16_bf16 v[34:49], v[90:93], v[86:89], v[34:49]
	s_waitcnt lgkmcnt(1)
	v_mfma_f32_32x32x16_bf16 v[18:33], v[90:93], v[182:185], v[18:33]
	v_add_f32_e32 v182, v97, v190
	v_add_f32_e32 v182, v66, v182
	v_add_f32_e32 v182, v67, v182
	v_add_f32_e32 v182, v68, v182
	v_add_f32_e32 v182, v69, v182
	v_add_f32_e32 v182, v70, v182
	v_add_f32_e32 v182, v71, v182
	s_waitcnt lgkmcnt(0)
	v_mfma_f32_32x32x16_bf16 v[2:17], v[90:93], v[192:195], v[2:17]
	ds_read2_b64 v[82:85], v187 offset0:24 offset1:26
	ds_read2_b64 v[86:89], v188 offset0:56 offset1:58
	ds_read2_b64 v[90:93], v189 offset0:88 offset1:90
	ds_read2_b64 v[94:97], v158 offset0:120 offset1:122
	v_add_f32_e32 v182, v72, v182
	v_cvt_pk_bf16_f32 v66, v66, v67
	v_cvt_pk_bf16_f32 v67, v68, v69
	v_cvt_pk_bf16_f32 v68, v70, v71
	v_cvt_pk_bf16_f32 v69, v72, v73
	v_exp_f32_e32 v74, v74
	v_exp_f32_e32 v75, v75
	s_waitcnt lgkmcnt(3)
	v_mfma_f32_32x32x16_bf16 v[50:65], v[66:69], v[82:85], v[50:65]
	v_exp_f32_e32 v76, v76
	v_exp_f32_e32 v77, v77
	v_exp_f32_e32 v78, v78
	v_exp_f32_e32 v79, v79
	v_exp_f32_e32 v80, v80
	v_exp_f32_e32 v81, v81
	s_waitcnt lgkmcnt(2)
	v_mfma_f32_32x32x16_bf16 v[34:49], v[66:69], v[86:89], v[34:49]
	s_waitcnt lgkmcnt(1)
	v_mfma_f32_32x32x16_bf16 v[18:33], v[66:69], v[90:93], v[18:33]
	v_add_f32_e32 v90, v73, v182
	v_add_f32_e32 v90, v74, v90
	v_add_f32_e32 v90, v75, v90
	v_add_f32_e32 v90, v76, v90
	v_add_f32_e32 v90, v77, v90
	v_add_f32_e32 v90, v78, v90
	v_add_f32_e32 v90, v79, v90
	s_waitcnt lgkmcnt(0)
	v_mfma_f32_32x32x16_bf16 v[2:17], v[66:69], v[94:97], v[2:17]
	ds_read2_b64 v[66:69], v187 offset0:28 offset1:30
	ds_read2_b64 v[70:73], v188 offset0:60 offset1:62
	ds_read2_b64 v[82:85], v189 offset0:92 offset1:94
	ds_read2_b64 v[86:89], v158 offset0:124 offset1:126
	v_add_f32_e32 v90, v80, v90
	v_cvt_pk_bf16_f32 v74, v74, v75
	v_cvt_pk_bf16_f32 v75, v76, v77
	v_cvt_pk_bf16_f32 v76, v78, v79
	v_cvt_pk_bf16_f32 v77, v80, v81
	s_waitcnt lgkmcnt(3)
	s_nop 0
	v_mfma_f32_32x32x16_bf16 v[50:65], v[74:77], v[66:69], v[50:65]
	v_add_f32_e32 v66, v81, v90
	v_add_f32_e32 v179, v179, v66
	v_cmp_lt_f32_e32 vcc, 0x43800000, v66
	s_waitcnt lgkmcnt(2)
	v_mfma_f32_32x32x16_bf16 v[34:49], v[74:77], v[70:73], v[34:49]
	s_waitcnt lgkmcnt(1)
	v_mfma_f32_32x32x16_bf16 v[18:33], v[74:77], v[82:85], v[18:33]
	s_waitcnt lgkmcnt(0)
	v_mfma_f32_32x32x16_bf16 v[2:17], v[74:77], v[86:89], v[2:17]
	s_cbranch_vccnz .Lrare_1
.Lback_1:
.LBB0_357:
	s_xor_b32 s62, s62, 1
	s_and_b64 vcc, exec, s[72:73]
	s_cbranch_vccz .LBB0_342
	s_mul_i32 s12, s62, 0x4800
	s_add_i32 s12, s12, 0
	v_add3_u32 v66, s12, v163, v164
	s_mul_i32 s13, s62, 0x3c00
	s_waitcnt vmcnt(5)
	ds_write_b128 v66, v[98:101]
	v_add3_u32 v66, s12, v165, v166
	s_add_i32 s12, s12, s13
	s_waitcnt vmcnt(4)
	ds_write_b128 v66, v[102:105]
	v_add_u32_e32 v66, s12, v167
	v_add3_u32 v66, v66, v168, s92
	s_waitcnt vmcnt(3)
	ds_write2_b64 v66, v[106:107], v[108:109] offset1:1
	v_add_u32_e32 v66, s12, v169
	v_add3_u32 v66, v66, v170, s92
	s_waitcnt vmcnt(2)
	ds_write2_b64 v66, v[110:111], v[112:113] offset1:1
	v_add_u32_e32 v66, s12, v171
	v_add3_u32 v66, v66, v172, s92
	s_waitcnt vmcnt(1)
	ds_write2_b64 v66, v[114:115], v[116:117] offset1:1
	v_add_u32_e32 v66, s12, v173
	v_add3_u32 v66, v66, v174, s92
	s_waitcnt vmcnt(0)
	ds_write2_b64 v66, v[118:119], v[120:121] offset1:1
	s_branch .LBB0_342

; __device__ __forceinline__ float swap32_max(float v) { auto rr = __builtin_amdgcn_permlane32_swap(__float_as_uint(v), __float_as_uint(v), false, false); return fmaxf(__uint_as_float(rr[0]), __uint_as_float(rr[1])); }
; template <int D, int DV, bool TAB, bool BITS, int KT> ...
;     ...
;             mx = swap32_max(mx);
;             if (__any(mx > 8.0f)) {
;                 const float dl = fmaxf(mx, 0.f); mhat += dl;
; #pragma unroll
;                 for (int r = 0; r < 16; ++r) { p0[r] -= dl; p1[r] -= dl; }
;                 const float alpha = __builtin_amdgcn_exp2f(-dl); l_run *= alpha;
;                 if (hi == 0) wsf[r32] = alpha;
;                 __builtin_amdgcn_fence(__ATOMIC_RELEASE, "wavefront"); __builtin_amdgcn_wave_barrier();
; #pragma unroll
;                 for (int j = 0; j < 4; ++j) { const f32x4 a4 = *(const f32x4*)(wsf + 8 * j + 4 * hi);
; #pragma unroll
;                     for (int dt = 0; dt < DV / 32; ++dt) { o[dt][4 * j + 0] *= a4[0]; o[dt][4 * j + 1] *= a4[1]; o[dt][4 * j + 2] *= a4[2]; o[dt][4 * j + 3] *= a4[3]; } }
;                 __builtin_amdgcn_fence(__ATOMIC_RELEASE, "wavefront"); __builtin_amdgcn_wave_barrier();
;             }
.Lrare_2:
	s_nop 11
	v_mov_b32_e32 v184, v66
	s_nop 1
	v_permlane32_swap_b32_e32 v66, v184
	v_add_f32_e32 v158, v66, v184
	v_log_f32_e32 v158, v158
	s_nop 0
	v_max_f32_e32 v158, v158, v158
	v_max_f32_e32 v158, 0, v158
	v_exp_f32_e64 v184, -v158
	s_and_saveexec_b64 s[10:11], s[6:7]
	ds_write_b32 v160, v184
	s_or_b64 exec, exec, s[10:11]
	ds_read_b128 v[192:195], v178
	ds_read_b128 v[196:199], v178 offset:32
	ds_read_b128 v[200:203], v178 offset:64
	ds_read_b128 v[204:207], v178 offset:96
	v_add_f32_e32 v181, v181, v158
	s_mov_b32 s100, 1
	v_mul_f32_e32 v163, v163, v184
	s_waitcnt lgkmcnt(0)
	v_pk_mul_f32 v[16:17], v[16:17], v[206:207]
	v_pk_mul_f32 v[12:13], v[12:13], v[202:203]
	v_pk_mul_f32 v[8:9], v[8:9], v[198:199]
	v_pk_mul_f32 v[4:5], v[4:5], v[194:195]
	v_pk_mul_f32 v[14:15], v[14:15], v[204:205]
	v_pk_mul_f32 v[10:11], v[10:11], v[200:201]
	v_pk_mul_f32 v[6:7], v[6:7], v[196:197]
	v_pk_mul_f32 v[2:3], v[2:3], v[192:193]
	v_pk_mul_f32 v[32:33], v[32:33], v[206:207]
	v_pk_mul_f32 v[28:29], v[28:29], v[202:203]
	v_pk_mul_f32 v[24:25], v[24:25], v[198:199]
	v_pk_mul_f32 v[20:21], v[20:21], v[194:195]
	v_pk_mul_f32 v[30:31], v[30:31], v[204:205]
	v_pk_mul_f32 v[26:27], v[26:27], v[200:201]
	v_pk_mul_f32 v[22:23], v[22:23], v[196:197]
	v_pk_mul_f32 v[18:19], v[18:19], v[192:193]
	v_pk_mul_f32 v[64:65], v[64:65], v[206:207]
	v_pk_mul_f32 v[60:61], v[60:61], v[202:203]
	v_pk_mul_f32 v[56:57], v[56:57], v[198:199]
	v_pk_mul_f32 v[52:53], v[52:53], v[194:195]
	v_pk_mul_f32 v[62:63], v[62:63], v[204:205]
	v_pk_mul_f32 v[58:59], v[58:59], v[200:201]
	v_pk_mul_f32 v[54:55], v[54:55], v[196:197]
	v_pk_mul_f32 v[50:51], v[50:51], v[192:193]
	v_pk_mul_f32 v[48:49], v[48:49], v[206:207]
	v_pk_mul_f32 v[44:45], v[44:45], v[202:203]
	v_pk_mul_f32 v[40:41], v[40:41], v[198:199]
	v_pk_mul_f32 v[36:37], v[36:37], v[194:195]
	v_pk_mul_f32 v[46:47], v[46:47], v[204:205]
	v_pk_mul_f32 v[42:43], v[42:43], v[200:201]
	v_pk_mul_f32 v[38:39], v[38:39], v[196:197]
	v_pk_mul_f32 v[34:35], v[34:35], v[192:193]
	s_branch .Lback_2
.Lrare_3:
	s_nop 11
	v_mov_b32_e32 v183, v66
	s_nop 1
	v_permlane32_swap_b32_e32 v66, v183
	v_add_f32_e32 v158, v66, v183
	v_log_f32_e32 v158, v158
	s_nop 0
	v_max_f32_e32 v158, v158, v158
	v_max_f32_e32 v158, 0, v158
	v_exp_f32_e64 v183, -v158
	s_and_saveexec_b64 s[10:11], s[6:7]
	ds_write_b32 v160, v183
	s_or_b64 exec, exec, s[10:11]
	ds_read_b128 v[192:195], v178
	ds_read_b128 v[196:199], v178 offset:32
	ds_read_b128 v[200:203], v178 offset:64
	ds_read_b128 v[204:207], v178 offset:96
	v_add_f32_e32 v181, v181, v158
	s_mov_b32 s100, 1
	v_mul_f32_e32 v163, v163, v183
	s_waitcnt lgkmcnt(0)
	v_pk_mul_f32 v[16:17], v[16:17], v[206:207]
	v_pk_mul_f32 v[12:13], v[12:13], v[202:203]
	v_pk_mul_f32 v[8:9], v[8:9], v[198:199]
	v_pk_mul_f32 v[4:5], v[4:5], v[194:195]
	v_pk_mul_f32 v[14:15], v[14:15], v[204:205]
	v_pk_mul_f32 v[10:11], v[10:11], v[200:201]
	v_pk_mul_f32 v[6:7], v[6:7], v[196:197]
	v_pk_mul_f32 v[2:3], v[2:3], v[192:193]
	v_pk_mul_f32 v[32:33], v[32:33], v[206:207]
	v_pk_mul_f32 v[28:29], v[28:29], v[202:203]
	v_pk_mul_f32 v[24:25], v[24:25], v[198:199]
	v_pk_mul_f32 v[20:21], v[20:21], v[194:195]
	v_pk_mul_f32 v[30:31], v[30:31], v[204:205]
	v_pk_mul_f32 v[26:27], v[26:27], v[200:201]
	v_pk_mul_f32 v[22:23], v[22:23], v[196:197]
	v_pk_mul_f32 v[18:19], v[18:19], v[192:193]
	v_pk_mul_f32 v[64:65], v[64:65], v[206:207]
	v_pk_mul_f32 v[60:61], v[60:61], v[202:203]
	v_pk_mul_f32 v[56:57], v[56:57], v[198:199]
	v_pk_mul_f32 v[52:53], v[52:53], v[194:195]
	v_pk_mul_f32 v[62:63], v[62:63], v[204:205]
	v_pk_mul_f32 v[58:59], v[58:59], v[200:201]
	v_pk_mul_f32 v[54:55], v[54:55], v[196:197]
	v_pk_mul_f32 v[50:51], v[50:51], v[192:193]
	v_pk_mul_f32 v[48:49], v[48:49], v[206:207]
	v_pk_mul_f32 v[44:45], v[44:45], v[202:203]
	v_pk_mul_f32 v[40:41], v[40:41], v[198:199]
	v_pk_mul_f32 v[36:37], v[36:37], v[194:195]
	v_pk_mul_f32 v[46:47], v[46:47], v[204:205]
	v_pk_mul_f32 v[42:43], v[42:43], v[200:201]
	v_pk_mul_f32 v[38:39], v[38:39], v[196:197]
	v_pk_mul_f32 v[34:35], v[34:35], v[192:193]
	s_branch .Lback_3

; __device__ __forceinline__ int crowc(int r) { return (r & 3) + 8 * (r >> 2); }
; template <int D, int DV, bool TAB, bool BITS, int KT> ...
;     ...
;             if (D == 64) {
;                 bf16x8 ka[4], kb[4];
;                 if (TAB) {
; #pragma unroll
;                     for (int r = 0; r < 16; ++r) p0[r] = tabL[tj + crowc(r)]; }
; #pragma unroll
;                 for (int kk = 0; kk < 4; ++kk) ka[kk] = *(const bf16x8*)(Kl + r32 * KP + (kk * 16 + 8 * hi) * 2);
;                 if (TAB) {
; #pragma unroll
;                     for (int r = 0; r < 16; ++r) p1[r] = tabL[tj + 32 + crowc(r)]; }
; #pragma unroll
;                 for (int kk = 0; kk < 4; ++kk) kb[kk] = *(const bf16x8*)(Kl + (32 + r32) * KP + (kk * 16 + 8 * hi) * 2);
;                 __builtin_amdgcn_sched_barrier(0);
; #pragma unroll
;                 for (int r = 0; r < 16; ++r) { if (TAB) p0[r] -= mhat; else p0[r] = nm; if (BITS) { if (!((w0 >> crowc(r)) & 1u)) p0[r] = NEGV; } }
;                 __builtin_amdgcn_sched_barrier(0);
; #pragma unroll
;                 for (int kk = 0; kk < 4; ++kk) p0 = __builtin_amdgcn_mfma_f32_32x32x16_bf16(ka[kk], qf[kk], p0, 0, 0, 0);
; #pragma unroll
;                 for (int r = 0; r < 16; ++r) { if (TAB) p1[r] -= mhat; else p1[r] = nm; if (BITS) { if (!((w1 >> crowc(r)) & 1u)) p1[r] = NEGV; } }
;                 __builtin_amdgcn_sched_barrier(0);
; #pragma unroll
;                 for (int kk = 0; kk < 4; ++kk) p1 = __builtin_amdgcn_mfma_f32_32x32x16_bf16(kb[kk], qf[kk], p1, 0, 0, 0);
;     ...
;             float rs = 0.f;
;             bf16x8 vc[DV / 32];
;     ...
; #pragma unroll
;             for (int g = 0; g < 4; ++g) {
;                 AT_VLOAD(vc, g);
;                 float e[8];
; #pragma unroll
;                 for (int i = 0; i < 8; ++i) { e[i] = __builtin_amdgcn_exp2f(g < 2 ? p0[(g & 1) * 8 + i] : p1[(g & 1) * 8 + i]); rs += e[i]; }
;                 u32x4v pw; pw.x = cvtpk(e[0], e[1]); pw.y = cvtpk(e[2], e[3]); pw.z = cvtpk(e[4], e[5]); pw.w = cvtpk(e[6], e[7]);
;                 const bf16x8 pa = __builtin_bit_cast(bf16x8, pw);
;                 __builtin_amdgcn_sched_barrier(0);
; #pragma unroll
;                 for (int dt = 0; dt < DV / 32; ++dt) o[dt] = __builtin_amdgcn_mfma_f32_32x32x16_bf16(pa, vc[dt], o[dt], 0, 0, 0);
;                 __builtin_amdgcn_sched_barrier(0x1 | 0x2 | 0x100);
;             }
;             l_run += rs;
.LBB0_372:
	v_exp_f32_e32 v82, v82
	v_exp_f32_e32 v83, v83
	v_exp_f32_e32 v84, v84
	v_exp_f32_e32 v85, v85
	v_add_u32_e32 v158, v182, v179
	v_add_f32_e32 v188, 0, v82
	v_exp_f32_e32 v86, v86
	v_add_u32_e32 v184, 0x9000, v158
	v_add_u32_e32 v185, 0xb000, v158
	v_add_u32_e32 v187, 0xd000, v158
	v_add_u32_e32 v158, 0xf000, v158
	v_add_f32_e32 v188, v83, v188
	v_exp_f32_e32 v87, v87
	ds_read2_b64 v[192:195], v184 offset1:2
	ds_read2_b64 v[196:199], v185 offset0:32 offset1:34
	ds_read2_b64 v[200:203], v187 offset0:64 offset1:66
	ds_read2_b64 v[204:207], v158 offset0:96 offset1:98
	v_add_f32_e32 v188, v84, v188
	v_exp_f32_e32 v88, v88
	v_exp_f32_e32 v89, v89
	v_add_f32_e32 v188, v85, v188
	v_add_f32_e32 v188, v86, v188
	v_add_f32_e32 v188, v87, v188
	v_add_f32_e32 v188, v88, v188
	v_cvt_pk_bf16_f32 v82, v82, v83
	v_cvt_pk_bf16_f32 v83, v84, v85
	v_cvt_pk_bf16_f32 v84, v86, v87
	v_cvt_pk_bf16_f32 v85, v88, v89
	v_exp_f32_e32 v90, v90
	v_exp_f32_e32 v91, v91
	s_waitcnt lgkmcnt(3)
	v_mfma_f32_32x32x16_bf16 v[2:17], v[82:85], v[192:195], v[2:17]
	v_exp_f32_e32 v92, v92
	v_add_f32_e32 v188, v89, v188
	v_exp_f32_e32 v93, v93
	v_add_f32_e32 v188, v90, v188
	v_exp_f32_e32 v94, v94
	v_add_f32_e32 v188, v91, v188
	v_exp_f32_e32 v95, v95
	s_waitcnt lgkmcnt(2)
	v_mfma_f32_32x32x16_bf16 v[18:33], v[82:85], v[196:199], v[18:33]
	v_add_f32_e32 v188, v92, v188
	v_exp_f32_e32 v96, v96
	v_exp_f32_e32 v97, v97
	v_add_f32_e32 v188, v93, v188
	v_add_f32_e32 v188, v94, v188
	v_add_f32_e32 v188, v95, v188
	v_add_f32_e32 v188, v96, v188
	s_waitcnt lgkmcnt(1)
	v_mfma_f32_32x32x16_bf16 v[50:65], v[82:85], v[200:203], v[50:65]
	v_cvt_pk_bf16_f32 v90, v90, v91
	v_cvt_pk_bf16_f32 v91, v92, v93
	v_cvt_pk_bf16_f32 v92, v94, v95
	v_cvt_pk_bf16_f32 v93, v96, v97
	s_waitcnt lgkmcnt(0)
	v_mfma_f32_32x32x16_bf16 v[34:49], v[82:85], v[204:207], v[34:49]
	ds_read2_b64 v[82:85], v184 offset0:4 offset1:6
	ds_read2_b64 v[86:89], v185 offset0:36 offset1:38
	ds_read2_b64 v[192:195], v187 offset0:68 offset1:70
	ds_read2_b64 v[196:199], v158 offset0:100 offset1:102
	v_exp_f32_e32 v66, v66
	v_exp_f32_e32 v67, v67
	s_waitcnt lgkmcnt(3)
	v_mfma_f32_32x32x16_bf16 v[2:17], v[90:93], v[82:85], v[2:17]
	v_exp_f32_e32 v68, v68
	v_add_f32_e32 v188, v97, v188
	v_exp_f32_e32 v69, v69
	v_add_f32_e32 v188, v66, v188
	v_exp_f32_e32 v70, v70
	v_add_f32_e32 v188, v67, v188
	v_exp_f32_e32 v71, v71
	s_waitcnt lgkmcnt(2)
	v_mfma_f32_32x32x16_bf16 v[18:33], v[90:93], v[86:89], v[18:33]
	v_add_f32_e32 v188, v68, v188
	v_exp_f32_e32 v72, v72
	v_exp_f32_e32 v73, v73
	v_add_f32_e32 v188, v69, v188
	v_add_f32_e32 v188, v70, v188
	v_add_f32_e32 v188, v71, v188
	v_add_f32_e32 v188, v72, v188
	s_waitcnt lgkmcnt(1)
	v_mfma_f32_32x32x16_bf16 v[50:65], v[90:93], v[192:195], v[50:65]
	v_cvt_pk_bf16_f32 v66, v66, v67
	v_cvt_pk_bf16_f32 v67, v68, v69
	v_cvt_pk_bf16_f32 v68, v70, v71
	v_cvt_pk_bf16_f32 v69, v72, v73
	s_waitcnt lgkmcnt(0)
	v_mfma_f32_32x32x16_bf16 v[34:49], v[90:93], v[196:199], v[34:49]
	ds_read2_b64 v[82:85], v184 offset0:8 offset1:10
	ds_read2_b64 v[86:89], v185 offset0:40 offset1:42
	ds_read2_b64 v[90:93], v187 offset0:72 offset1:74
	ds_read2_b64 v[94:97], v158 offset0:104 offset1:106
	v_exp_f32_e32 v74, v74
	v_exp_f32_e32 v75, v75
	s_waitcnt lgkmcnt(3)
	v_mfma_f32_32x32x16_bf16 v[2:17], v[66:69], v[82:85], v[2:17]
	v_exp_f32_e32 v76, v76
	v_exp_f32_e32 v77, v77
	v_exp_f32_e32 v78, v78
	v_exp_f32_e32 v79, v79
	v_exp_f32_e32 v80, v80
	v_exp_f32_e32 v81, v81
	s_waitcnt lgkmcnt(2)
	v_mfma_f32_32x32x16_bf16 v[18:33], v[66:69], v[86:89], v[18:33]
	s_waitcnt lgkmcnt(1)
	v_mfma_f32_32x32x16_bf16 v[50:65], v[66:69], v[90:93], v[50:65]
	v_add_f32_e32 v90, v73, v188
	v_add_f32_e32 v90, v74, v90
	v_add_f32_e32 v90, v75, v90
	v_add_f32_e32 v90, v76, v90
	v_add_f32_e32 v90, v77, v90
	v_add_f32_e32 v90, v78, v90
	v_add_f32_e32 v90, v79, v90
	s_waitcnt lgkmcnt(0)
	v_mfma_f32_32x32x16_bf16 v[34:49], v[66:69], v[94:97], v[34:49]
	ds_read2_b64 v[66:69], v184 offset0:12 offset1:14
	ds_read2_b64 v[70:73], v185 offset0:44 offset1:46
	ds_read2_b64 v[82:85], v187 offset0:76 offset1:78
	ds_read2_b64 v[86:89], v158 offset0:108 offset1:110
	v_add_f32_e32 v90, v80, v90
	v_cvt_pk_bf16_f32 v74, v74, v75
	v_cvt_pk_bf16_f32 v75, v76, v77
	v_cvt_pk_bf16_f32 v76, v78, v79
	v_cvt_pk_bf16_f32 v77, v80, v81
	s_waitcnt lgkmcnt(3)
	s_nop 0
	v_mfma_f32_32x32x16_bf16 v[2:17], v[74:77], v[66:69], v[2:17]
	v_add_f32_e32 v66, v81, v90
	v_add_f32_e32 v163, v163, v66
	v_cmp_lt_f32_e32 vcc, 0x43800000, v66
	s_waitcnt lgkmcnt(2)
	v_mfma_f32_32x32x16_bf16 v[18:33], v[74:77], v[70:73], v[18:33]
	s_waitcnt lgkmcnt(1)
	v_mfma_f32_32x32x16_bf16 v[50:65], v[74:77], v[82:85], v[50:65]
	s_waitcnt lgkmcnt(0)
	v_mfma_f32_32x32x16_bf16 v[34:49], v[74:77], v[86:89], v[34:49]
	s_cbranch_vccnz .Lrare_2
.Lback_2:
.LBB0_373:
	s_sub_i32 s10, s64, 64
	s_cmp_le_i32 s10, s25
	s_cselect_b64 s[10:11], -1, 0
	s_add_i32 s12, s64, -1
	s_cmp_ge_i32 s12, s62
	s_cselect_b64 s[12:13], -1, 0
	s_and_b64 s[10:11], s[10:11], s[12:13]
	s_andn2_b64 vcc, exec, s[10:11]
	s_cbranch_vccnz .LBB0_379
	s_cmp_lg_u32 s100, 0
	s_cbranch_scc1 .Lslow_qk_a2s1
	ds_read_b128 v[66:69], v183 offset:9216
	ds_read_b128 v[70:73], v183 offset:9248
	ds_read2_b32 v[90:91], v180 offset0:80 offset1:81
	ds_read2_b32 v[92:93], v180 offset0:82 offset1:83
	ds_read2_b32 v[94:95], v180 offset0:88 offset1:89
	ds_read2_b32 v[96:97], v180 offset0:90 offset1:91
	ds_read2_b32 v[82:83], v180 offset0:64 offset1:65
	ds_read2_b32 v[84:85], v180 offset0:66 offset1:67
	ds_read2_b32 v[86:87], v180 offset0:72 offset1:73
	ds_read2_b32 v[88:89], v180 offset0:74 offset1:75
	ds_read_b128 v[208:211], v183 offset:9280
	ds_read_b128 v[212:215], v183 offset:9312
	s_waitcnt lgkmcnt(2)
	v_mfma_f32_32x32x16_bf16 v[82:97], v[66:69], v[134:137], v[82:97]
	v_mfma_f32_32x32x16_bf16 v[82:97], v[70:73], v[130:133], v[82:97]
	ds_read_b128 v[192:195], v183 offset:13824
	ds_read_b128 v[196:199], v183 offset:13856
	ds_read_b128 v[200:203], v183 offset:13888
	ds_read_b128 v[204:207], v183 offset:13920
	ds_read2_b32 v[66:67], v180 offset0:96 offset1:97
	ds_read2_b32 v[68:69], v180 offset0:98 offset1:99
	ds_read2_b32 v[70:71], v180 offset0:104 offset1:105
	ds_read2_b32 v[72:73], v180 offset0:106 offset1:107
	ds_read2_b32 v[74:75], v180 offset0:112 offset1:113
	ds_read2_b32 v[76:77], v180 offset0:114 offset1:115
	ds_read2_b32 v[78:79], v180 offset0:120 offset1:121
	ds_read2_b32 v[80:81], v180 offset0:122 offset1:123
	s_waitcnt lgkmcnt(12)
	v_mfma_f32_32x32x16_bf16 v[82:97], v[208:211], v[126:129], v[82:97]
	v_mfma_f32_32x32x16_bf16 v[82:97], v[212:215], v[122:125], v[82:97]
	s_waitcnt lgkmcnt(0)
	v_mfma_f32_32x32x16_bf16 v[66:81], v[192:195], v[134:137], v[66:81]
	v_mfma_f32_32x32x16_bf16 v[66:81], v[196:199], v[130:133], v[66:81]
	v_mfma_f32_32x32x16_bf16 v[66:81], v[200:203], v[126:129], v[66:81]
	v_mfma_f32_32x32x16_bf16 v[66:81], v[204:207], v[122:125], v[66:81]

; __device__ __forceinline__ unsigned cvtpk(float lo, float hi) { f32x2_t v = {lo, hi}; bf16x2_t b = __builtin_convertvector(v, bf16x2_t); return __builtin_bit_cast(unsigned, b); }
; #define AT_VLOAD(dst, g) do { _Pragma("unroll") for (int dt = 0; dt < DV / 32; ++dt) { const unsigned char* vp = Vl + (dt * 32 + r32) * VP + (16 * (g) + 4 * hi) * 2; \
;                 const s16x4 lo = *(const s16x4*)vp, hh = *(const s16x4*)(vp + 16); dst[dt] = (bf16x8){lo[0], lo[1], lo[2], lo[3], hh[0], hh[1], hh[2], hh[3]}; } } while (0)
; template <int D, int DV, bool TAB, bool BITS, int KT> ...
;     ...
;             float rs = 0.f;
;             bf16x8 vc[DV / 32];
;     ...
; #pragma unroll
;             for (int g = 0; g < 4; ++g) {
;                 AT_VLOAD(vc, g);
;                 float e[8];
; #pragma unroll
;                 for (int i = 0; i < 8; ++i) { e[i] = __builtin_amdgcn_exp2f(g < 2 ? p0[(g & 1) * 8 + i] : p1[(g & 1) * 8 + i]); rs += e[i]; }
;                 u32x4v pw; pw.x = cvtpk(e[0], e[1]); pw.y = cvtpk(e[2], e[3]); pw.z = cvtpk(e[4], e[5]); pw.w = cvtpk(e[6], e[7]);
;                 const bf16x8 pa = __builtin_bit_cast(bf16x8, pw);
;                 __builtin_amdgcn_sched_barrier(0);
; #pragma unroll
;                 for (int dt = 0; dt < DV / 32; ++dt) o[dt] = __builtin_amdgcn_mfma_f32_32x32x16_bf16(pa, vc[dt], o[dt], 0, 0, 0);
;                 __builtin_amdgcn_sched_barrier(0x1 | 0x2 | 0x100);
;             }
;             l_run += rs;
;     ...
;         }
;         }
;         if (t + 1 < t_hi) AT_STORE(cur ^ 1);
.LBB0_378:
	v_exp_f32_e32 v82, v82
	v_exp_f32_e32 v83, v83
	v_exp_f32_e32 v84, v84
	v_exp_f32_e32 v85, v85
	v_add_u32_e32 v158, v182, v179
	v_add_f32_e32 v190, 0, v82
	v_exp_f32_e32 v86, v86
	v_add_u32_e32 v187, 0x9000, v158
	v_add_u32_e32 v188, 0xb000, v158
	v_add_u32_e32 v189, 0xd000, v158
	v_add_u32_e32 v158, 0xf000, v158
	v_add_f32_e32 v190, v83, v190
	v_exp_f32_e32 v87, v87
	ds_read2_b64 v[182:185], v187 offset0:16 offset1:18
	ds_read2_b64 v[192:195], v188 offset0:48 offset1:50
	ds_read2_b64 v[196:199], v189 offset0:80 offset1:82
	ds_read2_b64 v[200:203], v158 offset0:112 offset1:114
	v_add_f32_e32 v190, v84, v190
	v_exp_f32_e32 v88, v88
	v_exp_f32_e32 v89, v89
	v_add_f32_e32 v190, v85, v190
	v_add_f32_e32 v190, v86, v190
	v_add_f32_e32 v190, v87, v190
	v_add_f32_e32 v190, v88, v190
	v_cvt_pk_bf16_f32 v82, v82, v83
	v_cvt_pk_bf16_f32 v83, v84, v85
	v_cvt_pk_bf16_f32 v84, v86, v87
	v_cvt_pk_bf16_f32 v85, v88, v89
	v_exp_f32_e32 v90, v90
	v_exp_f32_e32 v91, v91
	s_waitcnt lgkmcnt(3)
	v_mfma_f32_32x32x16_bf16 v[2:17], v[82:85], v[182:185], v[2:17]
	v_exp_f32_e32 v92, v92
	v_add_f32_e32 v190, v89, v190
	v_exp_f32_e32 v93, v93
	v_add_f32_e32 v190, v90, v190
	v_exp_f32_e32 v94, v94
	v_add_f32_e32 v190, v91, v190
	v_exp_f32_e32 v95, v95
	s_waitcnt lgkmcnt(2)
	v_mfma_f32_32x32x16_bf16 v[18:33], v[82:85], v[192:195], v[18:33]
	v_add_f32_e32 v190, v92, v190
	v_exp_f32_e32 v96, v96
	v_exp_f32_e32 v97, v97
	v_add_f32_e32 v190, v93, v190
	v_add_f32_e32 v190, v94, v190
	v_add_f32_e32 v190, v95, v190
	v_add_f32_e32 v190, v96, v190
	s_waitcnt lgkmcnt(1)
	v_mfma_f32_32x32x16_bf16 v[50:65], v[82:85], v[196:199], v[50:65]
	v_cvt_pk_bf16_f32 v90, v90, v91
	v_cvt_pk_bf16_f32 v91, v92, v93
	v_cvt_pk_bf16_f32 v92, v94, v95
	v_cvt_pk_bf16_f32 v93, v96, v97
	s_waitcnt lgkmcnt(0)
	v_mfma_f32_32x32x16_bf16 v[34:49], v[82:85], v[200:203], v[34:49]
	ds_read2_b64 v[82:85], v187 offset0:20 offset1:22
	ds_read2_b64 v[86:89], v188 offset0:52 offset1:54
	ds_read2_b64 v[182:185], v189 offset0:84 offset1:86
	ds_read2_b64 v[192:195], v158 offset0:116 offset1:118
	v_exp_f32_e32 v66, v66
	v_exp_f32_e32 v67, v67
	s_waitcnt lgkmcnt(3)
	v_mfma_f32_32x32x16_bf16 v[2:17], v[90:93], v[82:85], v[2:17]
	v_exp_f32_e32 v68, v68
	v_exp_f32_e32 v69, v69
	v_exp_f32_e32 v70, v70
	v_exp_f32_e32 v71, v71
	v_exp_f32_e32 v72, v72
	v_exp_f32_e32 v73, v73
	s_waitcnt lgkmcnt(2)
	v_mfma_f32_32x32x16_bf16 v[18:33], v[90:93], v[86:89], v[18:33]
	s_waitcnt lgkmcnt(1)
	v_mfma_f32_32x32x16_bf16 v[50:65], v[90:93], v[182:185], v[50:65]
	v_add_f32_e32 v182, v97, v190
	v_add_f32_e32 v182, v66, v182
	v_add_f32_e32 v182, v67, v182
	v_add_f32_e32 v182, v68, v182
	v_add_f32_e32 v182, v69, v182
	v_add_f32_e32 v182, v70, v182
	v_add_f32_e32 v182, v71, v182
	s_waitcnt lgkmcnt(0)
	v_mfma_f32_32x32x16_bf16 v[34:49], v[90:93], v[192:195], v[34:49]
	ds_read2_b64 v[82:85], v187 offset0:24 offset1:26
	ds_read2_b64 v[86:89], v188 offset0:56 offset1:58
	ds_read2_b64 v[90:93], v189 offset0:88 offset1:90
	ds_read2_b64 v[94:97], v158 offset0:120 offset1:122
	v_add_f32_e32 v182, v72, v182
	v_cvt_pk_bf16_f32 v66, v66, v67
	v_cvt_pk_bf16_f32 v67, v68, v69
	v_cvt_pk_bf16_f32 v68, v70, v71
	v_cvt_pk_bf16_f32 v69, v72, v73
	v_exp_f32_e32 v74, v74
	v_exp_f32_e32 v75, v75
	s_waitcnt lgkmcnt(3)
	v_mfma_f32_32x32x16_bf16 v[2:17], v[66:69], v[82:85], v[2:17]
	v_exp_f32_e32 v76, v76
	v_exp_f32_e32 v77, v77
	v_exp_f32_e32 v78, v78
	v_exp_f32_e32 v79, v79
	v_exp_f32_e32 v80, v80
	v_exp_f32_e32 v81, v81
	s_waitcnt lgkmcnt(2)
	v_mfma_f32_32x32x16_bf16 v[18:33], v[66:69], v[86:89], v[18:33]
	s_waitcnt lgkmcnt(1)
	v_mfma_f32_32x32x16_bf16 v[50:65], v[66:69], v[90:93], v[50:65]
	v_add_f32_e32 v90, v73, v182
	v_add_f32_e32 v90, v74, v90
	v_add_f32_e32 v90, v75, v90
	v_add_f32_e32 v90, v76, v90
	v_add_f32_e32 v90, v77, v90
	v_add_f32_e32 v90, v78, v90
	v_add_f32_e32 v90, v79, v90
	s_waitcnt lgkmcnt(0)
	v_mfma_f32_32x32x16_bf16 v[34:49], v[66:69], v[94:97], v[34:49]
	ds_read2_b64 v[66:69], v187 offset0:28 offset1:30
	ds_read2_b64 v[70:73], v188 offset0:60 offset1:62
	ds_read2_b64 v[82:85], v189 offset0:92 offset1:94
	ds_read2_b64 v[86:89], v158 offset0:124 offset1:126
	v_add_f32_e32 v90, v80, v90
	v_cvt_pk_bf16_f32 v74, v74, v75
	v_cvt_pk_bf16_f32 v75, v76, v77
	v_cvt_pk_bf16_f32 v76, v78, v79
	v_cvt_pk_bf16_f32 v77, v80, v81
	s_waitcnt lgkmcnt(3)
	s_nop 0
	v_mfma_f32_32x32x16_bf16 v[2:17], v[74:77], v[66:69], v[2:17]
	v_add_f32_e32 v66, v81, v90
	v_add_f32_e32 v163, v163, v66
	v_cmp_lt_f32_e32 vcc, 0x43800000, v66
	s_waitcnt lgkmcnt(2)
	v_mfma_f32_32x32x16_bf16 v[18:33], v[74:77], v[70:73], v[18:33]
	s_waitcnt lgkmcnt(1)
	v_mfma_f32_32x32x16_bf16 v[50:65], v[74:77], v[82:85], v[50:65]
	s_waitcnt lgkmcnt(0)
	v_mfma_f32_32x32x16_bf16 v[34:49], v[74:77], v[86:89], v[34:49]
	s_cbranch_vccnz .Lrare_3
.Lback_3:
.LBB0_379:
	s_xor_b32 s63, s63, 1
	s_and_b64 vcc, exec, s[4:5]
	s_cbranch_vccz .LBB0_364
	s_mul_i32 s4, s63, 0x4800
	s_add_i32 s4, s4, 0
	v_add3_u32 v66, s4, v164, v165
	s_mul_i32 s5, s63, 0x3c00
	s_waitcnt vmcnt(5)
	ds_write_b128 v66, v[98:101]
	v_add3_u32 v66, s4, v166, v167
	s_add_i32 s4, s4, s5
	s_waitcnt vmcnt(4)
	ds_write_b128 v66, v[102:105]
	v_add_u32_e32 v66, s4, v168
	v_add3_u32 v66, v66, v169, s92
	s_waitcnt vmcnt(3)
	ds_write2_b64 v66, v[106:107], v[108:109] offset1:1
	v_add_u32_e32 v66, s4, v170
	v_add3_u32 v66, v66, v171, s92
	s_waitcnt vmcnt(2)
	ds_write2_b64 v66, v[110:111], v[112:113] offset1:1
	v_add_u32_e32 v66, s4, v172
	v_add3_u32 v66, v66, v173, s92
	s_waitcnt vmcnt(1)
	ds_write2_b64 v66, v[114:115], v[116:117] offset1:1
	v_add_u32_e32 v66, s4, v174
	v_add3_u32 v66, v66, v175, s92
	s_waitcnt vmcnt(0)
	ds_write2_b64 v66, v[118:119], v[120:121] offset1:1
	s_branch .LBB0_364

; __device__ __forceinline__ void idx_unit(unsigned char* lds, const bf16_t* P, int b, int qb16, unsigned* bits) {
;     ...
;     if (tid < 128) wl[tid] = bf2f(P[(tok0 + (tid >> 3)) * PW + P_IW + (tid & 7)]) * (0.35355339059327373f * 0.125f);
;     bf16x8 aq[4][4];
; #pragma unroll
;     for (int rb = 0; rb < 4; ++rb) { const bf16_t* ap = P + (tok0 + rb * 4 + (r32 >> 3)) * PW + P_IQ + (r32 & 7) * 64 + 8 * hi;
; #pragma unroll
;         for (int kk = 0; kk < 4; ++kk) aq[rb][kk] = *(const bf16x8*)(ap + kk * 16); }
;     __syncthreads();
;     f32x4 wreg[16];
; #pragma unroll
;     for (int q = 0; q < 16; ++q) wreg[q] = *(const f32x4*)(wl + q * 8 + 4 * hi);
;     bf16x8 bk[4], bn[4];
;     { const bf16_t* kp = P + (tokb + (wid < nblk ? wid : 0) * 32 + r32) * PW + P_IK + 8 * hi;
; #pragma unroll
;       for (int kk = 0; kk < 4; ++kk) { bk[kk] = *(const bf16x8*)(kp + kk * 16); bn[kk] = bk[kk]; } }
;     for (int blk = wid; blk < nblk; blk += 8) {
;         const int key = blk * 32 + r32;
;         if (blk + 8 < nblk) { const bf16_t* kp = P + (tokb + key + 256) * PW + P_IK + 8 * hi;
; #pragma unroll
;             for (int kk = 0; kk < 4; ++kk) bn[kk] = *(const bf16x8*)(kp + kk * 16); }
; #pragma unroll
;         for (int rb = 0; rb < 4; ++rb) {
;             f32x16 c;
; #pragma unroll
;             for (int r = 0; r < 16; ++r) c[r] = 0.f;
; #pragma unroll
;             for (int kk = 0; kk < 4; ++kk) c = __builtin_amdgcn_mfma_f32_32x32x16_bf16(aq[rb][kk], bk[kk], c, 0, 0, 0);
.LBB0_396:
	s_or_b64 exec, exec, s[0:1]
	v_bfe_u32 v0, v182, 3, 2
	v_or_b32_e32 v3, s70, v0
	v_mov_b64_e32 v[4:5], s[46:47]
	v_mad_u64_u32 v[6:7], s[0:1], v3, s37, v[4:5]
	v_lshlrev_b32_e32 v0, 7, v182
	v_bfe_u32 v2, v182, 5, 1
	v_mad_i32_i24 v7, s71, v236, v7
	v_and_b32_e32 v0, 0x380, v0
	v_lshl_add_u64 v[6:7], v[6:7], 0, v[0:1]
	v_lshlrev_b32_e32 v8, 4, v2
	v_mov_b32_e32 v9, v1
	v_lshl_add_u64 v[6:7], v[6:7], 0, v[8:9]
	s_mov_b64 s[10:11], 0x1000
	s_movk_i32 s6, 0x1000
	v_lshl_add_u64 v[10:11], v[6:7], 0, s[10:11]
	v_add_co_u32_e32 v6, vcc, s6, v6
	s_movk_i32 s5, 0x1000
	s_nop 0
	v_addc_co_u32_e32 v7, vcc, 0, v7, vcc
	global_load_dwordx4 v[18:21], v[10:11], off offset:32
	global_load_dwordx4 v[22:25], v[10:11], off offset:64
	global_load_dwordx4 v[26:29], v[6:7], off
	global_load_dwordx4 v[30:33], v[10:11], off offset:96
	v_or_b32_e32 v6, 4, v3
	v_mad_u64_u32 v[6:7], s[0:1], v6, s37, v[4:5]
	v_mad_i32_i24 v7, s71, v236, v7
	v_lshl_add_u64 v[6:7], v[6:7], 0, v[0:1]
	v_lshl_add_u64 v[6:7], v[6:7], 0, v[8:9]
	v_lshl_add_u64 v[10:11], v[6:7], 0, s[10:11]
	v_add_co_u32_e32 v6, vcc, s6, v6
	v_and_b32_e32 v178, 31, v182
	s_nop 0
	v_addc_co_u32_e32 v7, vcc, 0, v7, vcc
	global_load_dwordx4 v[34:37], v[10:11], off offset:32
	global_load_dwordx4 v[38:41], v[10:11], off offset:64
	global_load_dwordx4 v[42:45], v[6:7], off
	global_load_dwordx4 v[46:49], v[10:11], off offset:96
	v_or_b32_e32 v6, 8, v3
	v_mad_u64_u32 v[6:7], s[0:1], v6, s37, v[4:5]
	v_mad_i32_i24 v7, s71, v236, v7
	v_or_b32_e32 v3, 12, v3
	v_lshl_add_u64 v[6:7], v[6:7], 0, v[0:1]
	v_mad_u64_u32 v[4:5], s[0:1], v3, s37, v[4:5]
	v_lshl_add_u64 v[6:7], v[6:7], 0, v[8:9]
	v_mad_i32_i24 v5, s71, v236, v5
	v_lshl_add_u64 v[10:11], v[6:7], 0, s[10:11]
	v_add_co_u32_e32 v6, vcc, s6, v6
	v_lshl_add_u64 v[4:5], v[4:5], 0, v[0:1]
	s_nop 0
	v_addc_co_u32_e32 v7, vcc, 0, v7, vcc
	v_lshl_add_u64 v[4:5], v[4:5], 0, v[8:9]
	global_load_dwordx4 v[50:53], v[10:11], off offset:32
	global_load_dwordx4 v[54:57], v[10:11], off offset:64
	global_load_dwordx4 v[58:61], v[6:7], off
	global_load_dwordx4 v[62:65], v[10:11], off offset:96
	v_lshl_add_u64 v[6:7], v[4:5], 0, s[10:11]
	v_add_co_u32_e32 v4, vcc, 0x1000, v4
	s_add_i32 s0, s8, 47
	s_nop 0
	v_addc_co_u32_e32 v5, vcc, 0, v5, vcc
	global_load_dwordx4 v[66:69], v[6:7], off offset:32
	global_load_dwordx4 v[70:73], v[6:7], off offset:64
	global_load_dwordx4 v[74:77], v[4:5], off
	global_load_dwordx4 v[78:81], v[6:7], off offset:96
	s_ashr_i32 s1, s0, 31
	s_lshr_b32 s1, s1, 27
	s_add_i32 s0, s0, s1
	s_ashr_i32 s10, s4, 6
	s_ashr_i32 s9, s0, 5
	s_cmp_ge_i32 s10, s9
	v_mov_b32_e32 v179, v1
	s_waitcnt lgkmcnt(0)
	s_barrier
	s_cbranch_scc1 .LBB0_409
	s_lshl_b32 s6, s10, 5
	s_add_i32 s0, s6, s64
	v_lshlrev_b32_e32 v0, 3, v2
	v_or_b32_e32 v3, s0, v178
	v_mov_b64_e32 v[4:5], s[46:47]
	v_mad_i64_i32 v[4:5], s[0:1], v3, s37, v[4:5]
	v_lshlrev_b32_e32 v0, 1, v0
	v_lshl_add_u64 v[4:5], v[4:5], 0, v[0:1]
	s_mov_b64 s[0:1], 0x1400
	v_lshl_add_u64 v[6:7], v[4:5], 0, s[0:1]
	v_add_co_u32_e32 v4, vcc, s5, v4
	global_load_dwordx4 v[162:165], v[6:7], off offset:96
	global_load_dwordx4 v[166:169], v[6:7], off offset:64
	global_load_dwordx4 v[170:173], v[6:7], off offset:32
	v_addc_co_u32_e32 v5, vcc, 0, v5, vcc
	global_load_dwordx4 v[174:177], v[4:5], off offset:1024
	v_lshl_add_u32 v3, v2, 4, 0
	v_add_u32_e32 v3, 0x20000, v3
	ds_read_b128 v[82:85], v3 offset:480
	ds_read_b128 v[86:89], v3 offset:448
	ds_read_b128 v[90:93], v3 offset:416
	ds_read_b128 v[94:97], v3 offset:384
	ds_read_b128 v[98:101], v3 offset:352
	ds_read_b128 v[102:105], v3 offset:320
	ds_read_b128 v[106:109], v3 offset:288
	ds_read_b128 v[110:113], v3 offset:256
	ds_read_b128 v[114:117], v3 offset:224
	ds_read_b128 v[118:121], v3 offset:192
	ds_read_b128 v[122:125], v3 offset:160
	ds_read_b128 v[126:129], v3 offset:128
	ds_read_b128 v[130:133], v3 offset:96
	ds_read_b128 v[134:137], v3 offset:64
	ds_read_b128 v[138:141], v3
	ds_read_b128 v[142:145], v3 offset:32
	s_lshl_b32 s0, s10, 6
	v_cmp_eq_u32_e64 s[4:5], 0, v2
	v_lshl_or_b32 v183, v2, 1, s8
	v_lshl_add_u32 v2, v2, 14, s0
	s_add_i32 s1, 0, 0x10000
	v_lshl_or_b32 v2, v178, 1, v2
	v_or_b32_e32 v184, 1, v183
	v_or_b32_e32 v185, 4, v183
	v_or_b32_e32 v187, 5, v183
	v_or_b32_e32 v192, 8, v183
	v_or_b32_e32 v193, 9, v183
	v_or_b32_e32 v194, 12, v183
	v_or_b32_e32 v195, 13, v183
	v_or_b32_e32 v180, s6, v178
	v_add_u32_e32 v196, s1, v2
	s_mov_b32 s101, 0x8000
	v_add_u32_e32 v197, 0xffff0000, v196
	s_waitcnt vmcnt(3)
	v_mov_b64_e32 v[154:155], v[162:163]
	s_waitcnt vmcnt(2)
	v_mov_b64_e32 v[146:147], v[166:167]
	s_waitcnt vmcnt(1)
	v_mov_b64_e32 v[150:151], v[170:171]
	v_mov_b64_e32 v[156:157], v[164:165]
	v_mov_b64_e32 v[148:149], v[168:169]
	s_waitcnt vmcnt(0)
	v_mov_b64_e32 v[158:159], v[174:175]
	v_mov_b64_e32 v[152:153], v[172:173]
	v_mov_b64_e32 v[160:161], v[176:177]
	s_branch .Lidx_pro
.Lidx_pro:
	v_mfma_f32_32x32x16_bf16 v[2:17], v[26:29], v[174:177], 0
	v_mfma_f32_32x32x16_bf16 v[2:17], v[18:21], v[170:173], v[2:17]
	v_mfma_f32_32x32x16_bf16 v[2:17], v[22:25], v[166:169], v[2:17]
	v_mfma_f32_32x32x16_bf16 v[2:17], v[30:33], v[162:165], v[2:17]
	s_nop 11
.LBB0_399:
	s_add_i32 s10, s10, 8
	s_cmp_ge_i32 s10, s9
	s_cselect_b64 s[0:1], -1, 0
	s_and_b64 vcc, exec, s[0:1]
	s_cbranch_vccnz .Lidx_go
	v_ashrrev_i32_e32 v181, 31, v180
	v_lshl_add_u64 v[214:215], v[180:181], 0, s[64:65]
	v_mov_b64_e32 v[216:217], s[46:47]
	v_mad_u64_u32 v[216:217], s[6:7], v214, s37, v[216:217]
	v_mad_i32_i24 v217, v215, s37, v217
	v_lshl_add_u64 v[214:215], v[216:217], 0, v[0:1]
	s_mov_b64 s[6:7], 0x161400
	v_lshl_add_u64 v[216:217], v[214:215], 0, s[6:7]
	v_add_co_u32_e32 v214, vcc, 0x161000, v214
	s_nop 1
	v_addc_co_u32_e32 v215, vcc, 0, v215, vcc
	global_load_dwordx4 v[150:153], v[216:217], off offset:32
	global_load_dwordx4 v[146:149], v[216:217], off offset:64
	global_load_dwordx4 v[158:161], v[214:215], off offset:1024
	global_load_dwordx4 v[154:157], v[216:217], off offset:96
; #define IDX_TOT(j) ({ const f32x4 w4 = wreg[rb * 4 + (j)]; \
;                 const float part = w4[0] * reluf(c[4 * (j)]) + w4[1] * reluf(c[4 * (j) + 1]) + w4[2] * reluf(c[4 * (j) + 2]) + w4[3] * reluf(c[4 * (j) + 3]); swap32_add(part); })
; __device__ __forceinline__ void idx_unit(unsigned char* lds, const bf16_t* P, int b, int qb16, unsigned* bits) {
;     ...
;         for (int rb = 0; rb < 4; ++rb) {
;             f32x16 c;
; #pragma unroll
;             for (int r = 0; r < 16; ++r) c[r] = 0.f;
; #pragma unroll
;             for (int kk = 0; kk < 4; ++kk) c = __builtin_amdgcn_mfma_f32_32x32x16_bf16(aq[rb][kk], bk[kk], c, 0, 0, 0);
;             asm volatile("s_nop 15\n\ts_nop 7" : "+v"(c));
;             float tq0, tq1, tq2, tq3;
;     ...
;             tq0 = IDX_TOT(0); tq1 = IDX_TOT(1); tq2 = IDX_TOT(2); tq3 = IDX_TOT(3);
;     ...
;             const float ts0 = hi ? tq2 : tq0, ts1 = hi ? tq3 : tq1;
; #pragma unroll
;             for (int jj = 0; jj < 2; ++jj) { const float tv = jj ? ts1 : ts0; const int q = rb * 4 + 2 * hi + jj;
;                 unsigned short kv = 0;
;                 if (key <= t0 + q) { const _Float16 hv = (_Float16)tv; const unsigned short hb = __builtin_bit_cast(unsigned short, hv); kv = (hb & 0x8000u) ? (unsigned short)~hb : (unsigned short)(hb | 0x8000u); }
;                 sc[q * 4096 + key] = kv; }
.Lidx_go:
	s_waitcnt lgkmcnt(0)
	v_mfma_f32_32x32x16_bf16 v[198:213], v[42:45], v[174:177], 0
	v_max_f32_e32 v2, 0, v2
	v_max_f32_e32 v3, 0, v3
	v_max_f32_e32 v4, 0, v4
	v_max_f32_e32 v5, 0, v5
	v_max_f32_e32 v6, 0, v6
	v_max_f32_e32 v7, 0, v7
	v_max_f32_e32 v8, 0, v8
	v_max_f32_e32 v9, 0, v9
	v_mfma_f32_32x32x16_bf16 v[198:213], v[34:37], v[170:173], v[198:213]
	v_max_f32_e32 v10, 0, v10
	v_max_f32_e32 v11, 0, v11
	v_max_f32_e32 v12, 0, v12
	v_max_f32_e32 v13, 0, v13
	v_max_f32_e32 v14, 0, v14
	v_max_f32_e32 v15, 0, v15
	v_max_f32_e32 v16, 0, v16
	v_max_f32_e32 v17, 0, v17
	v_mfma_f32_32x32x16_bf16 v[198:213], v[38:41], v[166:169], v[198:213]
	v_pk_mul_f32 v[2:3], v[138:139], v[2:3]
	v_pk_mul_f32 v[6:7], v[142:143], v[6:7]
	v_pk_mul_f32 v[10:11], v[134:135], v[10:11]
	v_pk_mul_f32 v[14:15], v[130:131], v[14:15]
	v_pk_fma_f32 v[2:3], v[140:141], v[4:5], v[2:3]
	v_pk_fma_f32 v[6:7], v[144:145], v[8:9], v[6:7]
	v_pk_fma_f32 v[10:11], v[136:137], v[12:13], v[10:11]
	v_pk_fma_f32 v[14:15], v[132:133], v[16:17], v[14:15]
	v_mfma_f32_32x32x16_bf16 v[198:213], v[46:49], v[162:165], v[198:213]
	v_add_f32_e32 v3, v2, v3
	v_add_f32_e32 v7, v6, v7
	v_add_f32_e32 v11, v10, v11
	v_add_f32_e32 v15, v14, v15
	s_nop 0
	v_permlane32_swap_b32_e32 v3, v11
	s_nop 0
	v_permlane32_swap_b32_e32 v7, v15
	v_add_f32_e32 v3, v3, v11
	v_add_f32_e32 v7, v7, v15
	v_cvt_f16_f32_e32 v3, v3
	v_cvt_f16_f32_e32 v7, v7
	v_bfe_i32 v2, v3, 15, 1
	v_bfe_i32 v6, v7, 15, 1
	v_bitop3_b32 v3, v3, v2, s101 bitop3:0x1e
	v_bitop3_b32 v7, v7, v6, s101 bitop3:0x1e
	v_cmp_le_i32_e32 vcc, v180, v183
	v_cmp_le_i32_e64 s[6:7], v180, v184
	s_nop 0
	v_cndmask_b32_e32 v3, 0, v3, vcc
	v_cndmask_b32_e64 v7, 0, v7, s[6:7]
	ds_write_b16 v197, v3
	ds_write_b16 v197, v7 offset:8192
	v_mfma_f32_32x32x16_bf16 v[2:17], v[58:61], v[174:177], 0
	v_max_f32_e32 v198, 0, v198
	v_max_f32_e32 v199, 0, v199
	v_max_f32_e32 v200, 0, v200
	v_max_f32_e32 v201, 0, v201
	v_max_f32_e32 v202, 0, v202
	v_max_f32_e32 v203, 0, v203
	v_max_f32_e32 v204, 0, v204
	v_max_f32_e32 v205, 0, v205
	v_mfma_f32_32x32x16_bf16 v[2:17], v[50:53], v[170:173], v[2:17]
	v_max_f32_e32 v206, 0, v206
	v_max_f32_e32 v207, 0, v207
	v_max_f32_e32 v208, 0, v208
	v_max_f32_e32 v209, 0, v209
	v_max_f32_e32 v210, 0, v210
	v_max_f32_e32 v211, 0, v211
	v_max_f32_e32 v212, 0, v212
	v_max_f32_e32 v213, 0, v213
	v_mfma_f32_32x32x16_bf16 v[2:17], v[54:57], v[166:169], v[2:17]
	v_pk_mul_f32 v[198:199], v[126:127], v[198:199]
	v_pk_mul_f32 v[202:203], v[122:123], v[202:203]
	v_pk_mul_f32 v[206:207], v[118:119], v[206:207]
	v_pk_mul_f32 v[210:211], v[114:115], v[210:211]
	v_pk_fma_f32 v[198:199], v[128:129], v[200:201], v[198:199]
	v_pk_fma_f32 v[202:203], v[124:125], v[204:205], v[202:203]
	v_pk_fma_f32 v[206:207], v[120:121], v[208:209], v[206:207]
	v_pk_fma_f32 v[210:211], v[116:117], v[212:213], v[210:211]
	v_mfma_f32_32x32x16_bf16 v[2:17], v[62:65], v[162:165], v[2:17]
	v_add_f32_e32 v199, v198, v199
	v_add_f32_e32 v203, v202, v203
	v_add_f32_e32 v207, v206, v207
	v_add_f32_e32 v211, v210, v211
	s_nop 0
	v_permlane32_swap_b32_e32 v199, v207
	s_nop 0
	v_permlane32_swap_b32_e32 v203, v211
	v_add_f32_e32 v199, v199, v207
	v_add_f32_e32 v203, v203, v211
	v_cvt_f16_f32_e32 v199, v199
	v_cvt_f16_f32_e32 v203, v203
	v_bfe_i32 v198, v199, 15, 1
	v_bfe_i32 v202, v203, 15, 1
	v_bitop3_b32 v199, v199, v198, s101 bitop3:0x1e
	v_bitop3_b32 v203, v203, v202, s101 bitop3:0x1e
	v_cmp_le_i32_e32 vcc, v180, v185
	v_cmp_le_i32_e64 s[6:7], v180, v187
	s_nop 0
	v_cndmask_b32_e32 v199, 0, v199, vcc
	v_cndmask_b32_e64 v203, 0, v203, s[6:7]
	ds_write_b16 v197, v199 offset:32768
	ds_write_b16 v197, v203 offset:40960
	v_mfma_f32_32x32x16_bf16 v[198:213], v[74:77], v[174:177], 0
	v_max_f32_e32 v2, 0, v2
	v_max_f32_e32 v3, 0, v3
	v_max_f32_e32 v4, 0, v4
	v_max_f32_e32 v5, 0, v5
	v_max_f32_e32 v6, 0, v6
	v_max_f32_e32 v7, 0, v7
	v_max_f32_e32 v8, 0, v8
	v_max_f32_e32 v9, 0, v9
	v_mfma_f32_32x32x16_bf16 v[198:213], v[66:69], v[170:173], v[198:213]
	v_max_f32_e32 v10, 0, v10
	v_max_f32_e32 v11, 0, v11
	v_max_f32_e32 v12, 0, v12
	v_max_f32_e32 v13, 0, v13
	v_max_f32_e32 v14, 0, v14
	v_max_f32_e32 v15, 0, v15
	v_max_f32_e32 v16, 0, v16
	v_max_f32_e32 v17, 0, v17
	v_mfma_f32_32x32x16_bf16 v[198:213], v[70:73], v[166:169], v[198:213]
	v_pk_mul_f32 v[2:3], v[110:111], v[2:3]
	v_pk_mul_f32 v[6:7], v[106:107], v[6:7]
	v_pk_mul_f32 v[10:11], v[102:103], v[10:11]
	v_pk_mul_f32 v[14:15], v[98:99], v[14:15]
	v_pk_fma_f32 v[2:3], v[112:113], v[4:5], v[2:3]
	v_pk_fma_f32 v[6:7], v[108:109], v[8:9], v[6:7]
	v_pk_fma_f32 v[10:11], v[104:105], v[12:13], v[10:11]
	v_pk_fma_f32 v[14:15], v[100:101], v[16:17], v[14:15]
	v_mfma_f32_32x32x16_bf16 v[198:213], v[78:81], v[162:165], v[198:213]
	v_add_f32_e32 v3, v2, v3
	v_add_f32_e32 v7, v6, v7
	v_add_f32_e32 v11, v10, v11
	v_add_f32_e32 v15, v14, v15
	s_nop 0
	v_permlane32_swap_b32_e32 v3, v11
	s_nop 0
	v_permlane32_swap_b32_e32 v7, v15
	v_add_f32_e32 v3, v3, v11
	v_add_f32_e32 v7, v7, v15
	v_cvt_f16_f32_e32 v3, v3
	v_cvt_f16_f32_e32 v7, v7
	v_bfe_i32 v2, v3, 15, 1
	v_bfe_i32 v6, v7, 15, 1
	v_bitop3_b32 v3, v3, v2, s101 bitop3:0x1e
	v_bitop3_b32 v7, v7, v6, s101 bitop3:0x1e
	v_cmp_le_i32_e32 vcc, v180, v192
	v_cmp_le_i32_e64 s[6:7], v180, v193
	s_nop 0
	v_cndmask_b32_e32 v3, 0, v3, vcc
	v_cndmask_b32_e64 v7, 0, v7, s[6:7]
	ds_write_b16 v196, v3
	ds_write_b16 v196, v7 offset:8192
	s_waitcnt vmcnt(0)
; #define IDX_TOT(j) ({ const f32x4 w4 = wreg[rb * 4 + (j)]; \
;                 const float part = w4[0] * reluf(c[4 * (j)]) + w4[1] * reluf(c[4 * (j) + 1]) + w4[2] * reluf(c[4 * (j) + 2]) + w4[3] * reluf(c[4 * (j) + 3]); swap32_add(part); })
; __device__ __forceinline__ void idx_unit(unsigned char* lds, const bf16_t* P, int b, int qb16, unsigned* bits) {
;     ...
;         for (int rb = 0; rb < 4; ++rb) {
;             f32x16 c;
; #pragma unroll
;             for (int r = 0; r < 16; ++r) c[r] = 0.f;
; #pragma unroll
;             for (int kk = 0; kk < 4; ++kk) c = __builtin_amdgcn_mfma_f32_32x32x16_bf16(aq[rb][kk], bk[kk], c, 0, 0, 0);
;             asm volatile("s_nop 15\n\ts_nop 7" : "+v"(c));
;             float tq0, tq1, tq2, tq3;
;     ...
;             tq0 = IDX_TOT(0); tq1 = IDX_TOT(1); tq2 = IDX_TOT(2); tq3 = IDX_TOT(3);
;     ...
;             const float ts0 = hi ? tq2 : tq0, ts1 = hi ? tq3 : tq1;
; #pragma unroll
;             for (int jj = 0; jj < 2; ++jj) { const float tv = jj ? ts1 : ts0; const int q = rb * 4 + 2 * hi + jj;
;                 unsigned short kv = 0;
;                 if (key <= t0 + q) { const _Float16 hv = (_Float16)tv; const unsigned short hb = __builtin_bit_cast(unsigned short, hv); kv = (hb & 0x8000u) ? (unsigned short)~hb : (unsigned short)(hb | 0x8000u); }
;                 sc[q * 4096 + key] = kv; }
;         }
; #pragma unroll
;         for (int kk = 0; kk < 4; ++kk) bk[kk] = bn[kk];
	v_mov_b64_e32 v[162:163], v[154:155]
	v_mov_b64_e32 v[164:165], v[156:157]
	v_mov_b64_e32 v[166:167], v[146:147]
	v_mov_b64_e32 v[168:169], v[148:149]
	v_mov_b64_e32 v[170:171], v[150:151]
	v_mov_b64_e32 v[172:173], v[152:153]
	v_mov_b64_e32 v[174:175], v[158:159]
	v_mov_b64_e32 v[176:177], v[160:161]
	s_nop 1
	v_mfma_f32_32x32x16_bf16 v[2:17], v[26:29], v[174:177], 0
	v_max_f32_e32 v198, 0, v198
	v_max_f32_e32 v199, 0, v199
	v_max_f32_e32 v200, 0, v200
	v_max_f32_e32 v201, 0, v201
	v_max_f32_e32 v202, 0, v202
	v_max_f32_e32 v203, 0, v203
	v_max_f32_e32 v204, 0, v204
	v_max_f32_e32 v205, 0, v205
	v_mfma_f32_32x32x16_bf16 v[2:17], v[18:21], v[170:173], v[2:17]
	v_max_f32_e32 v206, 0, v206
	v_max_f32_e32 v207, 0, v207
	v_max_f32_e32 v208, 0, v208
	v_max_f32_e32 v209, 0, v209
	v_max_f32_e32 v210, 0, v210
	v_max_f32_e32 v211, 0, v211
	v_max_f32_e32 v212, 0, v212
	v_max_f32_e32 v213, 0, v213
	v_mfma_f32_32x32x16_bf16 v[2:17], v[22:25], v[166:169], v[2:17]
	v_pk_mul_f32 v[198:199], v[94:95], v[198:199]
	v_pk_mul_f32 v[202:203], v[90:91], v[202:203]
	v_pk_mul_f32 v[206:207], v[86:87], v[206:207]
	v_pk_mul_f32 v[210:211], v[82:83], v[210:211]
	v_pk_fma_f32 v[198:199], v[96:97], v[200:201], v[198:199]
	v_pk_fma_f32 v[202:203], v[92:93], v[204:205], v[202:203]
	v_pk_fma_f32 v[206:207], v[88:89], v[208:209], v[206:207]
	v_pk_fma_f32 v[210:211], v[84:85], v[212:213], v[210:211]
	v_mfma_f32_32x32x16_bf16 v[2:17], v[30:33], v[162:165], v[2:17]
	v_add_f32_e32 v199, v198, v199
	v_add_f32_e32 v203, v202, v203
	v_add_f32_e32 v207, v206, v207
	v_add_f32_e32 v211, v210, v211
	s_nop 0
	v_permlane32_swap_b32_e32 v199, v207
	s_nop 0
	v_permlane32_swap_b32_e32 v203, v211
	v_add_f32_e32 v199, v199, v207
	v_add_f32_e32 v203, v203, v211
	v_cvt_f16_f32_e32 v199, v199
	v_cvt_f16_f32_e32 v203, v203
	v_bfe_i32 v198, v199, 15, 1
	v_bfe_i32 v202, v203, 15, 1
	v_bitop3_b32 v199, v199, v198, s101 bitop3:0x1e
	v_bitop3_b32 v203, v203, v202, s101 bitop3:0x1e
	v_cmp_le_i32_e32 vcc, v180, v194
	v_cmp_le_i32_e64 s[6:7], v180, v195
	s_nop 0
	v_cndmask_b32_e32 v199, 0, v199, vcc
	v_cndmask_b32_e64 v203, 0, v203, s[6:7]
	ds_write_b16 v196, v199 offset:32768
	ds_write_b16 v196, v203 offset:40960
	v_add_u32_e32 v180, 0x100, v180
	v_add_u32_e32 v196, 0x200, v196
	v_add_u32_e32 v197, 0x200, v197
	s_and_b64 vcc, exec, s[0:1]
	s_cbranch_vccz .LBB0_399

; __device__ __forceinline__ float swap32_max(float v) { auto rr = __builtin_amdgcn_permlane32_swap(__float_as_uint(v), __float_as_uint(v), false, false); return fmaxf(__uint_as_float(rr[0]), __uint_as_float(rr[1])); }
; template <int D, int DV, bool TAB, bool BITS, int KT> ...
;     ...
;             mx = swap32_max(mx);
;             if (__any(mx > 8.0f)) {
;                 const float dl = fmaxf(mx, 0.f); mhat += dl;
; #pragma unroll
;                 for (int r = 0; r < 16; ++r) { p0[r] -= dl; p1[r] -= dl; }
;                 const float alpha = __builtin_amdgcn_exp2f(-dl); l_run *= alpha;
;                 if (hi == 0) wsf[r32] = alpha;
;                 __builtin_amdgcn_fence(__ATOMIC_RELEASE, "wavefront"); __builtin_amdgcn_wave_barrier();
; #pragma unroll
;                 for (int j = 0; j < 4; ++j) { const f32x4 a4 = *(const f32x4*)(wsf + 8 * j + 4 * hi);
; #pragma unroll
;                     for (int dt = 0; dt < DV / 32; ++dt) { o[dt][4 * j + 0] *= a4[0]; o[dt][4 * j + 1] *= a4[1]; o[dt][4 * j + 2] *= a4[2]; o[dt][4 * j + 3] *= a4[3]; } }
;                 __builtin_amdgcn_fence(__ATOMIC_RELEASE, "wavefront"); __builtin_amdgcn_wave_barrier();
;             }
.Lrare_4:
	s_nop 11
	v_mov_b32_e32 v128, v34
	s_nop 1
	v_permlane32_swap_b32_e32 v34, v128
	v_add_f32_e32 v106, v34, v128
	v_log_f32_e32 v106, v106
	s_nop 0
	v_max_f32_e32 v106, v106, v106
	v_max_f32_e32 v106, 0, v106
	v_exp_f32_e64 v128, -v106
	s_and_saveexec_b64 s[10:11], s[6:7]
	ds_write_b32 v108, v128
	s_or_b64 exec, exec, s[10:11]
	v_mul_f32_e32 v120, v120, v128
	ds_read_b128 v[128:131], v122
	ds_read_b128 v[132:135], v122 offset:32
	ds_read_b128 v[136:139], v122 offset:64
	ds_read_b128 v[140:143], v122 offset:96
	v_add_f32_e32 v125, v125, v106
	s_mov_b32 s100, 1
	s_waitcnt lgkmcnt(0)
	v_pk_mul_f32 v[16:17], v[16:17], v[142:143]
	v_pk_mul_f32 v[12:13], v[12:13], v[138:139]
	v_pk_mul_f32 v[8:9], v[8:9], v[134:135]
	v_pk_mul_f32 v[4:5], v[4:5], v[130:131]
	v_pk_mul_f32 v[32:33], v[32:33], v[142:143]
	v_pk_mul_f32 v[28:29], v[28:29], v[138:139]
	v_pk_mul_f32 v[24:25], v[24:25], v[134:135]
	v_pk_mul_f32 v[20:21], v[20:21], v[130:131]
	v_pk_mul_f32 v[14:15], v[14:15], v[140:141]
	v_pk_mul_f32 v[10:11], v[10:11], v[136:137]
	v_pk_mul_f32 v[6:7], v[6:7], v[132:133]
	v_pk_mul_f32 v[2:3], v[2:3], v[128:129]
	v_pk_mul_f32 v[30:31], v[30:31], v[140:141]
	v_pk_mul_f32 v[26:27], v[26:27], v[136:137]
	v_pk_mul_f32 v[22:23], v[22:23], v[132:133]
	v_pk_mul_f32 v[18:19], v[18:19], v[128:129]
	s_branch .Lback_4
.Lrare_5:
	s_nop 11
	v_mov_b32_e32 v127, v34
	s_nop 1
	v_permlane32_swap_b32_e32 v34, v127
	v_add_f32_e32 v106, v34, v127
	v_log_f32_e32 v106, v106
	s_nop 0
	v_max_f32_e32 v106, v106, v106
	v_max_f32_e32 v106, 0, v106
	v_exp_f32_e64 v127, -v106
	s_and_saveexec_b64 s[10:11], s[6:7]
	ds_write_b32 v108, v127
	s_or_b64 exec, exec, s[10:11]
	ds_read_b128 v[128:131], v122
	ds_read_b128 v[132:135], v122 offset:32
	ds_read_b128 v[136:139], v122 offset:64
	ds_read_b128 v[140:143], v122 offset:96
	v_add_f32_e32 v125, v125, v106
	s_mov_b32 s100, 1
	v_mul_f32_e32 v120, v120, v127
	s_waitcnt lgkmcnt(0)
	v_pk_mul_f32 v[16:17], v[16:17], v[142:143]
	v_pk_mul_f32 v[12:13], v[12:13], v[138:139]
	v_pk_mul_f32 v[8:9], v[8:9], v[134:135]
	v_pk_mul_f32 v[4:5], v[4:5], v[130:131]
	v_pk_mul_f32 v[32:33], v[32:33], v[142:143]
	v_pk_mul_f32 v[28:29], v[28:29], v[138:139]
	v_pk_mul_f32 v[24:25], v[24:25], v[134:135]
	v_pk_mul_f32 v[20:21], v[20:21], v[130:131]
	v_pk_mul_f32 v[14:15], v[14:15], v[140:141]
	v_pk_mul_f32 v[10:11], v[10:11], v[136:137]
	v_pk_mul_f32 v[6:7], v[6:7], v[132:133]
	v_pk_mul_f32 v[2:3], v[2:3], v[128:129]
	v_pk_mul_f32 v[30:31], v[30:31], v[140:141]
	v_pk_mul_f32 v[26:27], v[26:27], v[136:137]
	v_pk_mul_f32 v[22:23], v[22:23], v[132:133]
	v_pk_mul_f32 v[18:19], v[18:19], v[128:129]
	s_branch .Lback_5

; __device__ __forceinline__ int crowc(int r) { return (r & 3) + 8 * (r >> 2); }
; template <int D, int DV, bool TAB, bool BITS, int KT> ...
;     ...
;             if (D == 64) {
;                 bf16x8 ka[4], kb[4];
;                 if (TAB) {
; #pragma unroll
;                     for (int r = 0; r < 16; ++r) p0[r] = tabL[tj + crowc(r)]; }
; #pragma unroll
;                 for (int kk = 0; kk < 4; ++kk) ka[kk] = *(const bf16x8*)(Kl + r32 * KP + (kk * 16 + 8 * hi) * 2);
;                 if (TAB) {
; #pragma unroll
;                     for (int r = 0; r < 16; ++r) p1[r] = tabL[tj + 32 + crowc(r)]; }
; #pragma unroll
;                 for (int kk = 0; kk < 4; ++kk) kb[kk] = *(const bf16x8*)(Kl + (32 + r32) * KP + (kk * 16 + 8 * hi) * 2);
;                 __builtin_amdgcn_sched_barrier(0);
; #pragma unroll
;                 for (int r = 0; r < 16; ++r) { if (TAB) p0[r] -= mhat; else p0[r] = nm; if (BITS) { if (!((w0 >> crowc(r)) & 1u)) p0[r] = NEGV; } }
;                 __builtin_amdgcn_sched_barrier(0);
; #pragma unroll
;                 for (int kk = 0; kk < 4; ++kk) p0 = __builtin_amdgcn_mfma_f32_32x32x16_bf16(ka[kk], qf[kk], p0, 0, 0, 0);
; #pragma unroll
;                 for (int r = 0; r < 16; ++r) { if (TAB) p1[r] -= mhat; else p1[r] = nm; if (BITS) { if (!((w1 >> crowc(r)) & 1u)) p1[r] = NEGV; } }
;                 __builtin_amdgcn_sched_barrier(0);
; #pragma unroll
;                 for (int kk = 0; kk < 4; ++kk) p1 = __builtin_amdgcn_mfma_f32_32x32x16_bf16(kb[kk], qf[kk], p1, 0, 0, 0);
;     ...
;             float rs = 0.f;
;             bf16x8 vc[DV / 32];
;     ...
; #pragma unroll
;             for (int g = 0; g < 4; ++g) {
;                 AT_VLOAD(vc, g);
;                 float e[8];
; #pragma unroll
;                 for (int i = 0; i < 8; ++i) { e[i] = __builtin_amdgcn_exp2f(g < 2 ? p0[(g & 1) * 8 + i] : p1[(g & 1) * 8 + i]); rs += e[i]; }
;                 u32x4v pw; pw.x = cvtpk(e[0], e[1]); pw.y = cvtpk(e[2], e[3]); pw.z = cvtpk(e[4], e[5]); pw.w = cvtpk(e[6], e[7]);
;                 const bf16x8 pa = __builtin_bit_cast(bf16x8, pw);
;                 __builtin_amdgcn_sched_barrier(0);
; #pragma unroll
;                 for (int dt = 0; dt < DV / 32; ++dt) o[dt] = __builtin_amdgcn_mfma_f32_32x32x16_bf16(pa, vc[dt], o[dt], 0, 0, 0);
;                 __builtin_amdgcn_sched_barrier(0x1 | 0x2 | 0x100);
;             }
;             l_run += rs;
.LBB0_878:
	v_exp_f32_e32 v50, v50
	v_exp_f32_e32 v51, v51
	v_exp_f32_e32 v52, v52
	v_exp_f32_e32 v53, v53
	v_add_u32_e32 v106, v126, v123
	v_add_f32_e32 v137, 0, v50
	v_exp_f32_e32 v54, v54
	v_add_u32_e32 v136, 0x9000, v106
	v_add_u32_e32 v106, 0xb000, v106
	v_add_f32_e32 v137, v51, v137
	v_exp_f32_e32 v55, v55
	ds_read2_b64 v[128:131], v136 offset1:2
	ds_read2_b64 v[132:135], v106 offset0:32 offset1:34
	v_add_f32_e32 v137, v52, v137
	v_exp_f32_e32 v56, v56
	v_exp_f32_e32 v57, v57
	v_add_f32_e32 v137, v53, v137
	v_add_f32_e32 v137, v54, v137
	v_add_f32_e32 v137, v55, v137
	v_add_f32_e32 v137, v56, v137
	v_cvt_pk_bf16_f32 v50, v50, v51
	v_cvt_pk_bf16_f32 v51, v52, v53
	v_cvt_pk_bf16_f32 v52, v54, v55
	v_cvt_pk_bf16_f32 v53, v56, v57
	v_exp_f32_e32 v58, v58
	v_exp_f32_e32 v59, v59
	s_waitcnt lgkmcnt(1)
	v_mfma_f32_32x32x16_bf16 v[18:33], v[50:53], v[128:131], v[18:33]
	v_exp_f32_e32 v60, v60
	v_add_f32_e32 v128, v57, v137
	v_exp_f32_e32 v61, v61
	v_add_f32_e32 v128, v58, v128
	v_exp_f32_e32 v62, v62
	v_add_f32_e32 v128, v59, v128
	v_exp_f32_e32 v63, v63
	s_waitcnt lgkmcnt(0)
	v_mfma_f32_32x32x16_bf16 v[2:17], v[50:53], v[132:135], v[2:17]
	ds_read2_b64 v[50:53], v136 offset0:4 offset1:6
	ds_read2_b64 v[54:57], v106 offset0:36 offset1:38
	v_add_f32_e32 v128, v60, v128
	v_exp_f32_e32 v64, v64
	v_exp_f32_e32 v65, v65
	v_add_f32_e32 v128, v61, v128
	v_add_f32_e32 v128, v62, v128
	v_add_f32_e32 v128, v63, v128
	v_add_f32_e32 v128, v64, v128
	v_cvt_pk_bf16_f32 v58, v58, v59
	v_cvt_pk_bf16_f32 v59, v60, v61
	v_cvt_pk_bf16_f32 v60, v62, v63
	v_cvt_pk_bf16_f32 v61, v64, v65
	v_exp_f32_e32 v34, v34
	v_exp_f32_e32 v35, v35
	s_waitcnt lgkmcnt(1)
	v_mfma_f32_32x32x16_bf16 v[18:33], v[58:61], v[50:53], v[18:33]
	v_exp_f32_e32 v36, v36
	v_exp_f32_e32 v37, v37
	v_exp_f32_e32 v38, v38
	v_exp_f32_e32 v39, v39
	v_exp_f32_e32 v40, v40
	v_exp_f32_e32 v41, v41
	s_waitcnt lgkmcnt(0)
	v_mfma_f32_32x32x16_bf16 v[2:17], v[58:61], v[54:57], v[2:17]
	v_add_f32_e32 v58, v65, v128
	v_add_f32_e32 v58, v34, v58
	ds_read2_b64 v[50:53], v136 offset0:8 offset1:10
	ds_read2_b64 v[54:57], v106 offset0:40 offset1:42
	v_add_f32_e32 v58, v35, v58
	v_add_f32_e32 v58, v36, v58
	v_add_f32_e32 v58, v37, v58
	v_add_f32_e32 v58, v38, v58
	v_add_f32_e32 v58, v39, v58
	v_add_f32_e32 v58, v40, v58
	v_cvt_pk_bf16_f32 v34, v34, v35
	v_cvt_pk_bf16_f32 v35, v36, v37
	v_cvt_pk_bf16_f32 v36, v38, v39
	v_cvt_pk_bf16_f32 v37, v40, v41
	v_exp_f32_e32 v42, v42
	v_exp_f32_e32 v43, v43
	s_waitcnt lgkmcnt(1)
	v_mfma_f32_32x32x16_bf16 v[18:33], v[34:37], v[50:53], v[18:33]
	v_exp_f32_e32 v44, v44
	v_add_f32_e32 v50, v41, v58
	v_exp_f32_e32 v45, v45
	v_add_f32_e32 v50, v42, v50
	v_exp_f32_e32 v46, v46
	v_add_f32_e32 v50, v43, v50
	v_exp_f32_e32 v47, v47
	s_waitcnt lgkmcnt(0)
	v_mfma_f32_32x32x16_bf16 v[2:17], v[34:37], v[54:57], v[2:17]
	ds_read2_b64 v[34:37], v136 offset0:12 offset1:14
	ds_read2_b64 v[38:41], v106 offset0:44 offset1:46
	v_add_f32_e32 v50, v44, v50
	v_exp_f32_e32 v48, v48
	v_exp_f32_e32 v49, v49
	v_add_f32_e32 v50, v45, v50
	v_add_f32_e32 v50, v46, v50
	v_add_f32_e32 v50, v47, v50
	v_add_f32_e32 v50, v48, v50
	v_cvt_pk_bf16_f32 v42, v42, v43
	v_cvt_pk_bf16_f32 v43, v44, v45
	v_cvt_pk_bf16_f32 v44, v46, v47
	v_cvt_pk_bf16_f32 v45, v48, v49
	s_waitcnt lgkmcnt(1)
	s_nop 0
	v_mfma_f32_32x32x16_bf16 v[18:33], v[42:45], v[34:37], v[18:33]
	v_add_f32_e32 v34, v49, v50
	v_add_f32_e32 v120, v120, v34
	v_cmp_lt_f32_e32 vcc, 0x43800000, v34
	s_waitcnt lgkmcnt(0)
	v_mfma_f32_32x32x16_bf16 v[2:17], v[42:45], v[38:41], v[2:17]
	s_cbranch_vccnz .Lrare_4
.Lback_4:
.LBB0_879:
	s_cmp_le_i32 s74, s72
	s_cselect_b64 s[10:11], -1, 0
	s_add_i32 s12, s74, 63
	s_cmp_ge_i32 s12, s73
	s_cselect_b64 s[12:13], -1, 0
	s_and_b64 s[10:11], s[10:11], s[12:13]
	s_andn2_b64 vcc, exec, s[10:11]
	s_cbranch_vccnz .LBB0_885
	s_cmp_lg_u32 s100, 0
	s_cbranch_scc1 .Lslow_qk_bs1
	ds_read_b128 v[34:37], v127 offset:9216
	ds_read_b128 v[38:41], v127 offset:9248
	ds_read2_b32 v[58:59], v124 offset0:80 offset1:81
	ds_read2_b32 v[60:61], v124 offset0:82 offset1:83
	ds_read2_b32 v[62:63], v124 offset0:88 offset1:89
	ds_read2_b32 v[64:65], v124 offset0:90 offset1:91
	ds_read2_b32 v[50:51], v124 offset0:64 offset1:65
	ds_read2_b32 v[52:53], v124 offset0:66 offset1:67
	ds_read2_b32 v[54:55], v124 offset0:72 offset1:73
	ds_read2_b32 v[56:57], v124 offset0:74 offset1:75
	ds_read_b128 v[208:211], v127 offset:9280
	ds_read_b128 v[212:215], v127 offset:9312
	s_waitcnt lgkmcnt(2)
	v_mfma_f32_32x32x16_bf16 v[50:65], v[34:37], v[94:97], v[50:65]
	v_mfma_f32_32x32x16_bf16 v[50:65], v[38:41], v[90:93], v[50:65]
	ds_read_b128 v[128:131], v127 offset:13824
	ds_read_b128 v[132:135], v127 offset:13856
	ds_read_b128 v[136:139], v127 offset:13888
	ds_read_b128 v[140:143], v127 offset:13920
	ds_read2_b32 v[34:35], v124 offset0:96 offset1:97
	ds_read2_b32 v[36:37], v124 offset0:98 offset1:99
	ds_read2_b32 v[38:39], v124 offset0:104 offset1:105
	ds_read2_b32 v[40:41], v124 offset0:106 offset1:107
	ds_read2_b32 v[42:43], v124 offset0:112 offset1:113
	ds_read2_b32 v[44:45], v124 offset0:114 offset1:115
	ds_read2_b32 v[46:47], v124 offset0:120 offset1:121
	ds_read2_b32 v[48:49], v124 offset0:122 offset1:123
	s_waitcnt lgkmcnt(12)
	v_mfma_f32_32x32x16_bf16 v[50:65], v[208:211], v[86:89], v[50:65]
	v_mfma_f32_32x32x16_bf16 v[50:65], v[212:215], v[82:85], v[50:65]
	s_waitcnt lgkmcnt(0)
	v_mfma_f32_32x32x16_bf16 v[34:49], v[128:131], v[94:97], v[34:49]
	v_mfma_f32_32x32x16_bf16 v[34:49], v[132:135], v[90:93], v[34:49]
	v_mfma_f32_32x32x16_bf16 v[34:49], v[136:139], v[86:89], v[34:49]
	v_mfma_f32_32x32x16_bf16 v[34:49], v[140:143], v[82:85], v[34:49]

; __device__ __forceinline__ unsigned cvtpk(float lo, float hi) { f32x2_t v = {lo, hi}; bf16x2_t b = __builtin_convertvector(v, bf16x2_t); return __builtin_bit_cast(unsigned, b); }
; #define AT_VLOAD(dst, g) do { _Pragma("unroll") for (int dt = 0; dt < DV / 32; ++dt) { const unsigned char* vp = Vl + (dt * 32 + r32) * VP + (16 * (g) + 4 * hi) * 2; \
;                 const s16x4 lo = *(const s16x4*)vp, hh = *(const s16x4*)(vp + 16); dst[dt] = (bf16x8){lo[0], lo[1], lo[2], lo[3], hh[0], hh[1], hh[2], hh[3]}; } } while (0)
; template <int D, int DV, bool TAB, bool BITS, int KT> ...
;     ...
;             float rs = 0.f;
;             bf16x8 vc[DV / 32];
;     ...
; #pragma unroll
;             for (int g = 0; g < 4; ++g) {
;                 AT_VLOAD(vc, g);
;                 float e[8];
; #pragma unroll
;                 for (int i = 0; i < 8; ++i) { e[i] = __builtin_amdgcn_exp2f(g < 2 ? p0[(g & 1) * 8 + i] : p1[(g & 1) * 8 + i]); rs += e[i]; }
;                 u32x4v pw; pw.x = cvtpk(e[0], e[1]); pw.y = cvtpk(e[2], e[3]); pw.z = cvtpk(e[4], e[5]); pw.w = cvtpk(e[6], e[7]);
;                 const bf16x8 pa = __builtin_bit_cast(bf16x8, pw);
;                 __builtin_amdgcn_sched_barrier(0);
; #pragma unroll
;                 for (int dt = 0; dt < DV / 32; ++dt) o[dt] = __builtin_amdgcn_mfma_f32_32x32x16_bf16(pa, vc[dt], o[dt], 0, 0, 0);
;                 __builtin_amdgcn_sched_barrier(0x1 | 0x2 | 0x100);
;             }
;             l_run += rs;
;     ...
;         }
;         }
;         if (t + 1 < t_hi) AT_STORE(cur ^ 1);
.LBB0_884:
	v_exp_f32_e32 v50, v50
	v_exp_f32_e32 v51, v51
	v_exp_f32_e32 v52, v52
	v_exp_f32_e32 v53, v53
	v_add_u32_e32 v106, v126, v123
	v_add_f32_e32 v135, 0, v50
	v_exp_f32_e32 v54, v54
	v_add_u32_e32 v134, 0x9000, v106
	v_add_u32_e32 v106, 0xb000, v106
	v_add_f32_e32 v135, v51, v135
	v_exp_f32_e32 v55, v55
	ds_read2_b64 v[126:129], v134 offset0:16 offset1:18
	ds_read2_b64 v[130:133], v106 offset0:48 offset1:50
	v_add_f32_e32 v135, v52, v135
	v_exp_f32_e32 v56, v56
	v_exp_f32_e32 v57, v57
	v_add_f32_e32 v135, v53, v135
	v_add_f32_e32 v135, v54, v135
	v_add_f32_e32 v135, v55, v135
	v_add_f32_e32 v135, v56, v135
	v_cvt_pk_bf16_f32 v50, v50, v51
	v_cvt_pk_bf16_f32 v51, v52, v53
	v_cvt_pk_bf16_f32 v52, v54, v55
	v_cvt_pk_bf16_f32 v53, v56, v57
	v_exp_f32_e32 v58, v58
	v_exp_f32_e32 v59, v59
	s_waitcnt lgkmcnt(1)
	v_mfma_f32_32x32x16_bf16 v[18:33], v[50:53], v[126:129], v[18:33]
	v_exp_f32_e32 v60, v60
	v_add_f32_e32 v126, v57, v135
	v_exp_f32_e32 v61, v61
	v_add_f32_e32 v126, v58, v126
	v_exp_f32_e32 v62, v62
	v_add_f32_e32 v126, v59, v126
	v_exp_f32_e32 v63, v63
	s_waitcnt lgkmcnt(0)
	v_mfma_f32_32x32x16_bf16 v[2:17], v[50:53], v[130:133], v[2:17]
	ds_read2_b64 v[50:53], v134 offset0:20 offset1:22
	ds_read2_b64 v[54:57], v106 offset0:52 offset1:54
	v_add_f32_e32 v126, v60, v126
	v_exp_f32_e32 v64, v64
	v_exp_f32_e32 v65, v65
	v_add_f32_e32 v126, v61, v126
	v_add_f32_e32 v126, v62, v126
	v_add_f32_e32 v126, v63, v126
	v_add_f32_e32 v126, v64, v126
	v_cvt_pk_bf16_f32 v58, v58, v59
	v_cvt_pk_bf16_f32 v59, v60, v61
	v_cvt_pk_bf16_f32 v60, v62, v63
	v_cvt_pk_bf16_f32 v61, v64, v65
	v_exp_f32_e32 v34, v34
	v_exp_f32_e32 v35, v35
	s_waitcnt lgkmcnt(1)
	v_mfma_f32_32x32x16_bf16 v[18:33], v[58:61], v[50:53], v[18:33]
	v_exp_f32_e32 v36, v36
	v_exp_f32_e32 v37, v37
	v_exp_f32_e32 v38, v38
	v_exp_f32_e32 v39, v39
	v_exp_f32_e32 v40, v40
	v_exp_f32_e32 v41, v41
	s_waitcnt lgkmcnt(0)
	v_mfma_f32_32x32x16_bf16 v[2:17], v[58:61], v[54:57], v[2:17]
	v_add_f32_e32 v58, v65, v126
	v_add_f32_e32 v58, v34, v58
	ds_read2_b64 v[50:53], v134 offset0:24 offset1:26
	ds_read2_b64 v[54:57], v106 offset0:56 offset1:58
	v_add_f32_e32 v58, v35, v58
	v_add_f32_e32 v58, v36, v58
	v_add_f32_e32 v58, v37, v58
	v_add_f32_e32 v58, v38, v58
	v_add_f32_e32 v58, v39, v58
	v_add_f32_e32 v58, v40, v58
	v_cvt_pk_bf16_f32 v34, v34, v35
	v_cvt_pk_bf16_f32 v35, v36, v37
	v_cvt_pk_bf16_f32 v36, v38, v39
	v_cvt_pk_bf16_f32 v37, v40, v41
	v_exp_f32_e32 v42, v42
	v_exp_f32_e32 v43, v43
	s_waitcnt lgkmcnt(1)
	v_mfma_f32_32x32x16_bf16 v[18:33], v[34:37], v[50:53], v[18:33]
	v_exp_f32_e32 v44, v44
	v_add_f32_e32 v50, v41, v58
	v_exp_f32_e32 v45, v45
	v_add_f32_e32 v50, v42, v50
	v_exp_f32_e32 v46, v46
	v_add_f32_e32 v50, v43, v50
	v_exp_f32_e32 v47, v47
	s_waitcnt lgkmcnt(0)
	v_mfma_f32_32x32x16_bf16 v[2:17], v[34:37], v[54:57], v[2:17]
	ds_read2_b64 v[34:37], v134 offset0:28 offset1:30
	ds_read2_b64 v[38:41], v106 offset0:60 offset1:62
	v_add_f32_e32 v50, v44, v50
	v_exp_f32_e32 v48, v48
	v_exp_f32_e32 v49, v49
	v_add_f32_e32 v50, v45, v50
	v_add_f32_e32 v50, v46, v50
	v_add_f32_e32 v50, v47, v50
	v_add_f32_e32 v50, v48, v50
	v_cvt_pk_bf16_f32 v42, v42, v43
	v_cvt_pk_bf16_f32 v43, v44, v45
	v_cvt_pk_bf16_f32 v44, v46, v47
	v_cvt_pk_bf16_f32 v45, v48, v49
	s_waitcnt lgkmcnt(1)
	s_nop 0
	v_mfma_f32_32x32x16_bf16 v[18:33], v[42:45], v[34:37], v[18:33]
	v_add_f32_e32 v34, v49, v50
	v_add_f32_e32 v120, v120, v34
	v_cmp_lt_f32_e32 vcc, 0x43800000, v34
	s_waitcnt lgkmcnt(0)
	v_mfma_f32_32x32x16_bf16 v[2:17], v[42:45], v[38:41], v[2:17]
	s_cbranch_vccnz .Lrare_5
.Lback_5:
.LBB0_885:
	s_xor_b32 s71, s71, 1
	s_and_b64 vcc, exec, s[8:9]
	s_cbranch_vccz .LBB0_870
	s_mul_i32 s8, s71, 0x4800
	s_add_i32 s8, s8, 0
	v_add3_u32 v34, s8, v111, v112
	s_mul_i32 s9, s71, 0xfffffa00
	s_waitcnt vmcnt(3)
	ds_write_b128 v34, v[66:69]
	v_add3_u32 v34, s8, v113, v114
	s_add_i32 s8, s8, s9
	s_waitcnt vmcnt(2)
	ds_write_b128 v34, v[70:73]
	v_add_u32_e32 v34, s8, v115
	v_add3_u32 v34, v34, v116, s92
	s_waitcnt vmcnt(1)
	ds_write2_b64 v34, v[74:75], v[76:77] offset1:1
	v_add_u32_e32 v34, s8, v117
	v_add3_u32 v34, v34, v118, s92
	s_waitcnt vmcnt(0)
	ds_write2_b64 v34, v[78:79], v[80:81] offset1:1
	s_branch .LBB0_870

; __device__ __forceinline__ float swap32_max(float v) { auto rr = __builtin_amdgcn_permlane32_swap(__float_as_uint(v), __float_as_uint(v), false, false); return fmaxf(__uint_as_float(rr[0]), __uint_as_float(rr[1])); }
; template <int D, int DV, bool TAB, bool BITS, int KT> ...
;     ...
;             mx = swap32_max(mx);
;             if (__any(mx > 8.0f)) {
;                 const float dl = fmaxf(mx, 0.f); mhat += dl;
; #pragma unroll
;                 for (int r = 0; r < 16; ++r) { p0[r] -= dl; p1[r] -= dl; }
;                 const float alpha = __builtin_amdgcn_exp2f(-dl); l_run *= alpha;
;                 if (hi == 0) wsf[r32] = alpha;
;                 __builtin_amdgcn_fence(__ATOMIC_RELEASE, "wavefront"); __builtin_amdgcn_wave_barrier();
; #pragma unroll
;                 for (int j = 0; j < 4; ++j) { const f32x4 a4 = *(const f32x4*)(wsf + 8 * j + 4 * hi);
; #pragma unroll
;                     for (int dt = 0; dt < DV / 32; ++dt) { o[dt][4 * j + 0] *= a4[0]; o[dt][4 * j + 1] *= a4[1]; o[dt][4 * j + 2] *= a4[2]; o[dt][4 * j + 3] *= a4[3]; } }
;                 __builtin_amdgcn_fence(__ATOMIC_RELEASE, "wavefront"); __builtin_amdgcn_wave_barrier();
;             }
.Lrare_6:
	s_nop 11
	v_mov_b32_e32 v103, v34
	s_nop 1
	v_permlane32_swap_b32_e32 v34, v103
	v_add_f32_e32 v102, v34, v103
	v_log_f32_e32 v102, v102
	s_nop 0
	v_max_f32_e32 v102, v102, v102
	v_max_f32_e32 v102, 0, v102
	v_exp_f32_e64 v103, -v102
	s_and_saveexec_b64 s[70:71], s[6:7]
	ds_write_b32 v121, v103
	s_or_b64 exec, exec, s[70:71]
	ds_read_b128 v[142:145], v136
	ds_read_b128 v[146:149], v136 offset:32
	ds_read_b128 v[150:153], v136 offset:64
	ds_read_b128 v[154:157], v136 offset:96
	v_add_f32_e32 v139, v139, v102
	v_mul_f32_e32 v133, v133, v103
	s_waitcnt lgkmcnt(0)
	v_pk_mul_f32 v[16:17], v[16:17], v[156:157]
	v_pk_mul_f32 v[12:13], v[12:13], v[152:153]
	v_pk_mul_f32 v[8:9], v[8:9], v[148:149]
	v_pk_mul_f32 v[4:5], v[4:5], v[144:145]
	v_pk_mul_f32 v[32:33], v[32:33], v[156:157]
	v_pk_mul_f32 v[28:29], v[28:29], v[152:153]
	v_pk_mul_f32 v[24:25], v[24:25], v[148:149]
	v_pk_mul_f32 v[20:21], v[20:21], v[144:145]
	v_pk_mul_f32 v[14:15], v[14:15], v[154:155]
	v_pk_mul_f32 v[10:11], v[10:11], v[150:151]
	v_pk_mul_f32 v[6:7], v[6:7], v[146:147]
	v_pk_mul_f32 v[2:3], v[2:3], v[142:143]
	v_pk_mul_f32 v[30:31], v[30:31], v[154:155]
	v_pk_mul_f32 v[26:27], v[26:27], v[150:151]
	v_pk_mul_f32 v[22:23], v[22:23], v[146:147]
	v_pk_mul_f32 v[18:19], v[18:19], v[142:143]
	s_branch .Lback_6
.Lrare_7:
	s_nop 11
	v_mov_b32_e32 v103, v34
	s_nop 1
	v_permlane32_swap_b32_e32 v34, v103
	v_add_f32_e32 v102, v34, v103
	v_log_f32_e32 v102, v102
	s_nop 0
	v_max_f32_e32 v102, v102, v102
	v_max_f32_e32 v102, 0, v102
	v_exp_f32_e64 v103, -v102
	s_and_saveexec_b64 s[70:71], s[6:7]
	ds_write_b32 v121, v103
	s_or_b64 exec, exec, s[70:71]
	v_add_f32_e32 v139, v139, v102
	v_mul_f32_e32 v133, v133, v103
	ds_read_b128 v[102:105], v136
	ds_read_b128 v[142:145], v136 offset:32
	ds_read_b128 v[146:149], v136 offset:64
	ds_read_b128 v[150:153], v136 offset:96
	s_waitcnt lgkmcnt(3)
	v_pk_mul_f32 v[4:5], v[4:5], v[104:105]
	s_waitcnt lgkmcnt(2)
	v_pk_mul_f32 v[8:9], v[8:9], v[144:145]
	s_waitcnt lgkmcnt(1)
	v_pk_mul_f32 v[12:13], v[12:13], v[148:149]
	s_waitcnt lgkmcnt(0)
	v_pk_mul_f32 v[16:17], v[16:17], v[152:153]
	v_pk_mul_f32 v[32:33], v[32:33], v[152:153]
	v_pk_mul_f32 v[28:29], v[28:29], v[148:149]
	v_pk_mul_f32 v[24:25], v[24:25], v[144:145]
	v_pk_mul_f32 v[20:21], v[20:21], v[104:105]
	v_pk_mul_f32 v[14:15], v[14:15], v[150:151]
	v_pk_mul_f32 v[10:11], v[10:11], v[146:147]
	v_pk_mul_f32 v[6:7], v[6:7], v[142:143]
	v_pk_mul_f32 v[2:3], v[2:3], v[102:103]
	v_pk_mul_f32 v[30:31], v[30:31], v[150:151]
	v_pk_mul_f32 v[26:27], v[26:27], v[146:147]
	v_pk_mul_f32 v[22:23], v[22:23], v[142:143]
	v_pk_mul_f32 v[18:19], v[18:19], v[102:103]
	s_branch .Lback_7

; __device__ __forceinline__ unsigned cvtpk(float lo, float hi) { f32x2_t v = {lo, hi}; bf16x2_t b = __builtin_convertvector(v, bf16x2_t); return __builtin_bit_cast(unsigned, b); }
; __device__ __forceinline__ int crowc(int r) { return (r & 3) + 8 * (r >> 2); }
; #define AT_VLOAD(dst, g) do { _Pragma("unroll") for (int dt = 0; dt < DV / 32; ++dt) { const unsigned char* vp = Vl + (dt * 32 + r32) * VP + (16 * (g) + 4 * hi) * 2; \
;                 const s16x4 lo = *(const s16x4*)vp, hh = *(const s16x4*)(vp + 16); dst[dt] = (bf16x8){lo[0], lo[1], lo[2], lo[3], hh[0], hh[1], hh[2], hh[3]}; } } while (0)
; template <int D, int DV, bool TAB, bool BITS, int KT> ...
;     ...
;                 if (TAB) {
; #pragma unroll
;                     for (int r = 0; r < 16; ++r) p0[r] = tabL[tj + crowc(r)];
; #pragma unroll
;                     for (int r = 0; r < 16; ++r) p1[r] = tabL[tj + 32 + crowc(r)];
;                     __builtin_amdgcn_sched_barrier(0);
; #pragma unroll
;                     for (int r = 0; r < 16; ++r) { p0[r] -= mhat; p1[r] -= mhat; }
;                 } else {
; #pragma unroll
;                     for (int r = 0; r < 16; ++r) { p0[r] = nm; p1[r] = nm; }
;                 }
;                 if (BITS) {
; #pragma unroll
;                     for (int r = 0; r < 16; ++r) { const int off = crowc(r); if (!((w0 >> off) & 1u)) p0[r] = NEGV; if (!((w1 >> off) & 1u)) p1[r] = NEGV; } }
;     ...
;             float rs = 0.f;
;             bf16x8 vc[DV / 32];
;     ...
; #pragma unroll
;             for (int g = 0; g < 4; ++g) {
;                 AT_VLOAD(vc, g);
;                 float e[8];
; #pragma unroll
;                 for (int i = 0; i < 8; ++i) { e[i] = __builtin_amdgcn_exp2f(g < 2 ? p0[(g & 1) * 8 + i] : p1[(g & 1) * 8 + i]); rs += e[i]; }
;                 u32x4v pw; pw.x = cvtpk(e[0], e[1]); pw.y = cvtpk(e[2], e[3]); pw.z = cvtpk(e[4], e[5]); pw.w = cvtpk(e[6], e[7]);
;                 const bf16x8 pa = __builtin_bit_cast(bf16x8, pw);
;                 __builtin_amdgcn_sched_barrier(0);
; #pragma unroll
;                 for (int dt = 0; dt < DV / 32; ++dt) o[dt] = __builtin_amdgcn_mfma_f32_32x32x16_bf16(pa, vc[dt], o[dt], 0, 0, 0);
;                 __builtin_amdgcn_sched_barrier(0x1 | 0x2 | 0x100);
;             }
;             l_run += rs;
.LBB0_957:
	v_exp_f32_e32 v50, v50
	v_exp_f32_e32 v51, v51
	v_exp_f32_e32 v52, v52
	v_exp_f32_e32 v53, v53
	v_add_u32_e32 v102, v140, v137
	v_add_f32_e32 v150, 0, v50
	v_exp_f32_e32 v54, v54
	v_add_u32_e32 v103, 0x9000, v102
	v_add_u32_e32 v102, 0xb000, v102
	v_add_f32_e32 v150, v51, v150
	v_exp_f32_e32 v55, v55
	ds_read2_b64 v[142:145], v103 offset1:2
	ds_read2_b64 v[146:149], v102 offset0:32 offset1:34
	v_add_f32_e32 v150, v52, v150
	v_exp_f32_e32 v56, v56
	v_exp_f32_e32 v57, v57
	v_add_f32_e32 v150, v53, v150
	v_add_f32_e32 v150, v54, v150
	v_add_f32_e32 v150, v55, v150
	v_add_f32_e32 v150, v56, v150
	v_cvt_pk_bf16_f32 v50, v50, v51
	v_cvt_pk_bf16_f32 v51, v52, v53
	v_cvt_pk_bf16_f32 v52, v54, v55
	v_cvt_pk_bf16_f32 v53, v56, v57
	v_exp_f32_e32 v58, v58
	v_exp_f32_e32 v59, v59
	s_waitcnt lgkmcnt(1)
	v_mfma_f32_32x32x16_bf16 v[18:33], v[50:53], v[142:145], v[18:33]
	v_exp_f32_e32 v60, v60
	v_add_f32_e32 v142, v57, v150
	v_exp_f32_e32 v61, v61
	v_add_f32_e32 v142, v58, v142
	v_exp_f32_e32 v62, v62
	v_add_f32_e32 v142, v59, v142
	v_exp_f32_e32 v63, v63
	s_waitcnt lgkmcnt(0)
	v_mfma_f32_32x32x16_bf16 v[2:17], v[50:53], v[146:149], v[2:17]
	ds_read2_b64 v[50:53], v103 offset0:4 offset1:6
	ds_read2_b64 v[54:57], v102 offset0:36 offset1:38
	v_add_f32_e32 v142, v60, v142
	v_exp_f32_e32 v64, v64
	v_exp_f32_e32 v65, v65
	v_add_f32_e32 v142, v61, v142
	v_add_f32_e32 v142, v62, v142
	v_add_f32_e32 v142, v63, v142
	v_add_f32_e32 v142, v64, v142
	v_cvt_pk_bf16_f32 v58, v58, v59
	v_cvt_pk_bf16_f32 v59, v60, v61
	v_cvt_pk_bf16_f32 v60, v62, v63
	v_cvt_pk_bf16_f32 v61, v64, v65
	v_exp_f32_e32 v34, v34
	v_exp_f32_e32 v35, v35
	s_waitcnt lgkmcnt(1)
	v_mfma_f32_32x32x16_bf16 v[18:33], v[58:61], v[50:53], v[18:33]
	v_exp_f32_e32 v36, v36
	v_exp_f32_e32 v37, v37
	v_exp_f32_e32 v38, v38
	v_exp_f32_e32 v39, v39
	v_exp_f32_e32 v40, v40
	v_exp_f32_e32 v41, v41
	s_waitcnt lgkmcnt(0)
	v_mfma_f32_32x32x16_bf16 v[2:17], v[58:61], v[54:57], v[2:17]
	v_add_f32_e32 v58, v65, v142
	v_add_f32_e32 v58, v34, v58
	ds_read2_b64 v[50:53], v103 offset0:8 offset1:10
	ds_read2_b64 v[54:57], v102 offset0:40 offset1:42
	v_add_f32_e32 v58, v35, v58
	v_add_f32_e32 v58, v36, v58
	v_add_f32_e32 v58, v37, v58
	v_add_f32_e32 v58, v38, v58
	v_add_f32_e32 v58, v39, v58
	v_add_f32_e32 v58, v40, v58
	v_cvt_pk_bf16_f32 v34, v34, v35
	v_cvt_pk_bf16_f32 v35, v36, v37
	v_cvt_pk_bf16_f32 v36, v38, v39
	v_cvt_pk_bf16_f32 v37, v40, v41
	v_exp_f32_e32 v42, v42
	v_exp_f32_e32 v43, v43
	s_waitcnt lgkmcnt(1)
	v_mfma_f32_32x32x16_bf16 v[18:33], v[34:37], v[50:53], v[18:33]
	v_exp_f32_e32 v44, v44
	v_add_f32_e32 v50, v41, v58
	v_exp_f32_e32 v45, v45
	v_add_f32_e32 v50, v42, v50
	v_exp_f32_e32 v46, v46
	v_add_f32_e32 v50, v43, v50
	v_exp_f32_e32 v47, v47
	s_waitcnt lgkmcnt(0)
	v_mfma_f32_32x32x16_bf16 v[2:17], v[34:37], v[54:57], v[2:17]
	ds_read2_b64 v[34:37], v103 offset0:12 offset1:14
	ds_read2_b64 v[38:41], v102 offset0:44 offset1:46
	v_add_f32_e32 v50, v44, v50
	v_exp_f32_e32 v48, v48
	v_exp_f32_e32 v49, v49
	v_add_f32_e32 v50, v45, v50
	v_add_f32_e32 v50, v46, v50
	v_add_f32_e32 v50, v47, v50
	v_add_f32_e32 v50, v48, v50
	v_cvt_pk_bf16_f32 v42, v42, v43
	v_cvt_pk_bf16_f32 v43, v44, v45
	v_cvt_pk_bf16_f32 v44, v46, v47
	v_cvt_pk_bf16_f32 v45, v48, v49
	s_waitcnt lgkmcnt(1)
	s_nop 0
	v_mfma_f32_32x32x16_bf16 v[18:33], v[42:45], v[34:37], v[18:33]
	v_add_f32_e32 v34, v49, v50
	v_add_f32_e32 v133, v133, v34
	v_cmp_lt_f32_e32 vcc, 0x43800000, v34
	s_waitcnt lgkmcnt(0)
	v_mfma_f32_32x32x16_bf16 v[2:17], v[42:45], v[38:41], v[2:17]
	s_cbranch_vccnz .Lrare_6
.Lback_6:
.LBB0_958:
	s_sub_i32 s9, s64, 64
	s_cmp_le_i32 s9, s73
	s_cselect_b64 s[12:13], -1, 0
	s_add_i32 s9, s64, -1
	s_cmp_ge_i32 s9, s74
	s_cselect_b64 s[52:53], -1, 0
	s_and_b64 s[12:13], s[12:13], s[52:53]
	s_andn2_b64 vcc, exec, s[12:13]
	s_cbranch_vccnz .LBB0_964
	ds_read2_b32 v[34:35], v138 offset0:64 offset1:67
	ds_read2_b32 v[36:37], v138 offset0:65 offset1:66
	ds_read2_b32 v[38:39], v138 offset0:72 offset1:73
	ds_read2_b32 v[40:41], v138 offset0:74 offset1:75
	ds_read2_b32 v[42:43], v138 offset0:80 offset1:81
	ds_read_b128 v[142:145], v141 offset:9216
	ds_read_b128 v[146:149], v141 offset:9248
	ds_read_b128 v[150:153], v141 offset:9280
	ds_read_b128 v[154:157], v141 offset:9312
	ds_read2_b32 v[44:45], v138 offset0:96 offset1:99
	ds_read2_b32 v[46:47], v138 offset0:82 offset1:83
	ds_read2_b32 v[48:49], v138 offset0:88 offset1:89
	ds_read2_b32 v[64:65], v138 offset0:90 offset1:91
	s_waitcnt vmcnt(0)
	ds_read2_b32 v[102:103], v138 offset0:97 offset1:98
	ds_read2_b32 v[174:175], v138 offset0:104 offset1:105
	ds_read2_b32 v[176:177], v138 offset0:106 offset1:107
	ds_read2_b32 v[178:179], v138 offset0:112 offset1:113
	ds_read2_b32 v[180:181], v138 offset0:114 offset1:115
	ds_read2_b32 v[182:183], v138 offset0:120 offset1:121
	ds_read2_b32 v[184:185], v138 offset0:122 offset1:123
	ds_read_b128 v[158:161], v141 offset:13824
	ds_read_b128 v[162:165], v141 offset:13856
	ds_read_b128 v[166:169], v141 offset:13888
	ds_read_b128 v[170:173], v141 offset:13920
	v_lshrrev_b32_e32 v104, v134, v104
	v_and_b32_e32 v50, 1, v104
	s_waitcnt lgkmcnt(14)
; __device__ __forceinline__ int crowc(int r) { return (r & 3) + 8 * (r >> 2); }
; template <int D, int DV, bool TAB, bool BITS, int KT> ...
;     ...
;                 if (TAB) {
; #pragma unroll
;                     for (int r = 0; r < 16; ++r) p0[r] = tabL[tj + crowc(r)];
; #pragma unroll
;                     for (int r = 0; r < 16; ++r) p1[r] = tabL[tj + 32 + crowc(r)];
;                     __builtin_amdgcn_sched_barrier(0);
; #pragma unroll
;                     for (int r = 0; r < 16; ++r) { p0[r] -= mhat; p1[r] -= mhat; }
;                 } else {
; #pragma unroll
;                     for (int r = 0; r < 16; ++r) { p0[r] = nm; p1[r] = nm; }
;                 }
;                 if (BITS) {
; #pragma unroll
;                     for (int r = 0; r < 16; ++r) { const int off = crowc(r); if (!((w0 >> off) & 1u)) p0[r] = NEGV; if (!((w1 >> off) & 1u)) p1[r] = NEGV; } }
; #pragma unroll
;                 for (int k4 = 0; k4 < D / 16; k4 += KG) {
;                     bf16x8 ka[KG], kb[KG];
; #pragma unroll
;                     for (int kk = 0; kk < KG; ++kk) { ka[kk] = *(const bf16x8*)(Kl + r32 * KP + ((k4 + kk) * 16 + 8 * hi) * 2); kb[kk] = *(const bf16x8*)(Kl + (32 + r32) * KP + ((k4 + kk) * 16 + 8 * hi) * 2); }
;                     __builtin_amdgcn_sched_barrier(0);
; #pragma unroll
;                     for (int kk = 0; kk < KG; ++kk) { p0 = __builtin_amdgcn_mfma_f32_32x32x16_bf16(ka[kk], qf[k4 + kk], p0, 0, 0, 0); p1 = __builtin_amdgcn_mfma_f32_32x32x16_bf16(kb[kk], qf[k4 + kk], p1, 0, 0, 0); }
;                     __builtin_amdgcn_sched_barrier(0);
;                 }
	v_sub_f32_e32 v34, v34, v139
	v_cmp_eq_u32_e32 vcc, 1, v50
	s_nop 1
	v_cndmask_b32_e32 v50, v237, v34, vcc
	v_sub_f32_e32 v34, v36, v139
	v_and_b32_e32 v36, 2, v104
	v_cmp_ne_u32_e32 vcc, 0, v36
	v_and_b32_e32 v36, 4, v104
	s_nop 0
	v_cndmask_b32_e32 v51, v237, v34, vcc
	v_sub_f32_e32 v34, v37, v139
	v_cmp_ne_u32_e32 vcc, 0, v36
	s_nop 1
	v_cndmask_b32_e32 v52, v237, v34, vcc
	v_sub_f32_e32 v34, v35, v139
	v_and_b32_e32 v35, 8, v104
	v_cmp_ne_u32_e32 vcc, 0, v35
	v_and_b32_e32 v35, 0x100, v104
	s_nop 0
	v_cndmask_b32_e32 v53, v237, v34, vcc
	v_sub_f32_e32 v34, v38, v139
	v_cmp_ne_u32_e32 vcc, 0, v35
	v_and_b32_e32 v35, 0x200, v104
	s_nop 0
	v_cndmask_b32_e32 v54, v237, v34, vcc
	v_sub_f32_e32 v34, v39, v139
	v_cmp_ne_u32_e32 vcc, 0, v35
	v_and_b32_e32 v35, 0x400, v104
	s_nop 0
	v_cndmask_b32_e32 v55, v237, v34, vcc
	v_sub_f32_e32 v34, v40, v139
	v_cmp_ne_u32_e32 vcc, 0, v35
	v_and_b32_e32 v35, 0x800, v104
	s_nop 0
	v_cndmask_b32_e32 v56, v237, v34, vcc
	v_sub_f32_e32 v34, v41, v139
	v_cmp_ne_u32_e32 vcc, 0, v35
	v_and_b32_e32 v35, 0x10000, v104
	s_nop 0
	v_cndmask_b32_e32 v57, v237, v34, vcc
	v_sub_f32_e32 v34, v42, v139
	v_cmp_ne_u32_e32 vcc, 0, v35
	v_and_b32_e32 v35, 0x20000, v104
	s_nop 0
	v_cndmask_b32_e32 v58, v237, v34, vcc
	v_sub_f32_e32 v34, v43, v139
	v_cmp_ne_u32_e32 vcc, 0, v35
	v_and_b32_e32 v35, 0x40000, v104
	s_nop 0
	v_cndmask_b32_e32 v59, v237, v34, vcc
	s_waitcnt lgkmcnt(13)
	v_sub_f32_e32 v34, v46, v139
	v_cmp_ne_u32_e32 vcc, 0, v35
	v_and_b32_e32 v35, 0x80000, v104
	s_nop 0
	v_cndmask_b32_e32 v60, v237, v34, vcc
	v_sub_f32_e32 v34, v47, v139
	v_cmp_ne_u32_e32 vcc, 0, v35
	v_and_b32_e32 v35, 0x1000000, v104
	s_nop 0
	v_cndmask_b32_e32 v61, v237, v34, vcc
	s_waitcnt lgkmcnt(12)
	v_sub_f32_e32 v34, v48, v139
	v_cmp_ne_u32_e32 vcc, 0, v35
	v_and_b32_e32 v35, 0x2000000, v104
	s_nop 0
	v_cndmask_b32_e32 v62, v237, v34, vcc
	v_sub_f32_e32 v34, v49, v139
	v_cmp_ne_u32_e32 vcc, 0, v35
	v_and_b32_e32 v35, 0x4000000, v104
	s_nop 0
	v_cndmask_b32_e32 v63, v237, v34, vcc
	s_waitcnt lgkmcnt(11)
	v_sub_f32_e32 v34, v64, v139
	v_cmp_ne_u32_e32 vcc, 0, v35
	v_and_b32_e32 v35, 0x8000000, v104
	s_nop 0
	v_cndmask_b32_e32 v64, v237, v34, vcc
	v_sub_f32_e32 v34, v65, v139
	v_cmp_ne_u32_e32 vcc, 0, v35
	s_nop 1
	v_cndmask_b32_e32 v65, v237, v34, vcc
	v_lshrrev_b32_e32 v49, v134, v105
	v_and_b32_e32 v35, 1, v49
	v_sub_f32_e32 v34, v44, v139
	v_cmp_eq_u32_e32 vcc, 1, v35
	v_and_b32_e32 v36, 2, v49
	s_waitcnt lgkmcnt(10)
	v_sub_f32_e32 v35, v102, v139
	v_cndmask_b32_e32 v34, v237, v34, vcc
	v_cmp_ne_u32_e32 vcc, 0, v36
	v_and_b32_e32 v37, 4, v49
	v_sub_f32_e32 v36, v103, v139
	v_cndmask_b32_e32 v35, v237, v35, vcc
	v_cmp_ne_u32_e32 vcc, 0, v37
	v_and_b32_e32 v38, 8, v49
	v_sub_f32_e32 v37, v45, v139
	v_cndmask_b32_e32 v36, v237, v36, vcc
	v_cmp_ne_u32_e32 vcc, 0, v38
	v_and_b32_e32 v39, 0x100, v49
	s_waitcnt lgkmcnt(9)
	v_sub_f32_e32 v38, v174, v139
	v_cndmask_b32_e32 v37, v237, v37, vcc
	v_cmp_ne_u32_e32 vcc, 0, v39
	v_and_b32_e32 v40, 0x200, v49
	v_sub_f32_e32 v39, v175, v139
	v_cndmask_b32_e32 v38, v237, v38, vcc
	v_cmp_ne_u32_e32 vcc, 0, v40
	v_and_b32_e32 v41, 0x400, v49
	s_waitcnt lgkmcnt(8)
	v_sub_f32_e32 v40, v176, v139
	v_cndmask_b32_e32 v39, v237, v39, vcc
	v_cmp_ne_u32_e32 vcc, 0, v41
	v_and_b32_e32 v42, 0x800, v49
	v_sub_f32_e32 v41, v177, v139
	v_cndmask_b32_e32 v40, v237, v40, vcc
	v_cmp_ne_u32_e32 vcc, 0, v42
	v_and_b32_e32 v43, 0x10000, v49
	s_waitcnt lgkmcnt(7)
	v_sub_f32_e32 v42, v178, v139
	v_cndmask_b32_e32 v41, v237, v41, vcc
	v_cmp_ne_u32_e32 vcc, 0, v43
	v_and_b32_e32 v44, 0x20000, v49
	v_sub_f32_e32 v43, v179, v139
	v_cndmask_b32_e32 v42, v237, v42, vcc
	v_cmp_ne_u32_e32 vcc, 0, v44
	v_and_b32_e32 v45, 0x40000, v49
	s_waitcnt lgkmcnt(6)
	v_sub_f32_e32 v44, v180, v139
	v_cndmask_b32_e32 v43, v237, v43, vcc
	v_cmp_ne_u32_e32 vcc, 0, v45
	v_and_b32_e32 v46, 0x80000, v49
	v_sub_f32_e32 v45, v181, v139
	v_cndmask_b32_e32 v44, v237, v44, vcc
	v_cmp_ne_u32_e32 vcc, 0, v46
	v_and_b32_e32 v47, 0x1000000, v49
	s_waitcnt lgkmcnt(5)
	v_sub_f32_e32 v46, v182, v139
	v_cndmask_b32_e32 v45, v237, v45, vcc
	v_cmp_ne_u32_e32 vcc, 0, v47
	v_and_b32_e32 v48, 0x2000000, v49
	v_sub_f32_e32 v47, v183, v139
	v_cndmask_b32_e32 v46, v237, v46, vcc
	v_cmp_ne_u32_e32 vcc, 0, v48
	v_and_b32_e32 v102, 0x4000000, v49
	s_waitcnt lgkmcnt(4)
	v_sub_f32_e32 v48, v184, v139
	v_cndmask_b32_e32 v47, v237, v47, vcc
	v_cmp_ne_u32_e32 vcc, 0, v102
	v_and_b32_e32 v49, 0x8000000, v49
	v_sub_f32_e32 v102, v185, v139
	v_cndmask_b32_e32 v48, v237, v48, vcc
	v_cmp_ne_u32_e32 vcc, 0, v49
	s_nop 1
	v_cndmask_b32_e32 v49, v237, v102, vcc
	s_waitcnt lgkmcnt(3)
	s_nop 0
	v_mfma_f32_32x32x16_bf16 v[34:49], v[158:161], v[94:97], v[34:49]
	v_mfma_f32_32x32x16_bf16 v[50:65], v[142:145], v[94:97], v[50:65]
	s_waitcnt lgkmcnt(2)
	v_mfma_f32_32x32x16_bf16 v[34:49], v[162:165], v[90:93], v[34:49]
	v_mfma_f32_32x32x16_bf16 v[50:65], v[146:149], v[90:93], v[50:65]
	s_waitcnt lgkmcnt(1)
	v_mfma_f32_32x32x16_bf16 v[34:49], v[166:169], v[86:89], v[34:49]
	v_mfma_f32_32x32x16_bf16 v[50:65], v[150:153], v[86:89], v[50:65]
	s_waitcnt lgkmcnt(0)
	v_mfma_f32_32x32x16_bf16 v[34:49], v[170:173], v[82:85], v[34:49]
	v_mfma_f32_32x32x16_bf16 v[50:65], v[154:157], v[82:85], v[50:65]
	s_nop 11
; __device__ __forceinline__ unsigned cvtpk(float lo, float hi) { f32x2_t v = {lo, hi}; bf16x2_t b = __builtin_convertvector(v, bf16x2_t); return __builtin_bit_cast(unsigned, b); }
; #define AT_VLOAD(dst, g) do { _Pragma("unroll") for (int dt = 0; dt < DV / 32; ++dt) { const unsigned char* vp = Vl + (dt * 32 + r32) * VP + (16 * (g) + 4 * hi) * 2; \
;                 const s16x4 lo = *(const s16x4*)vp, hh = *(const s16x4*)(vp + 16); dst[dt] = (bf16x8){lo[0], lo[1], lo[2], lo[3], hh[0], hh[1], hh[2], hh[3]}; } } while (0)
; template <int D, int DV, bool TAB, bool BITS, int KT> ...
;     ...
;             float rs = 0.f;
;             bf16x8 vc[DV / 32];
;     ...
; #pragma unroll
;             for (int g = 0; g < 4; ++g) {
;                 AT_VLOAD(vc, g);
;                 float e[8];
; #pragma unroll
;                 for (int i = 0; i < 8; ++i) { e[i] = __builtin_amdgcn_exp2f(g < 2 ? p0[(g & 1) * 8 + i] : p1[(g & 1) * 8 + i]); rs += e[i]; }
;                 u32x4v pw; pw.x = cvtpk(e[0], e[1]); pw.y = cvtpk(e[2], e[3]); pw.z = cvtpk(e[4], e[5]); pw.w = cvtpk(e[6], e[7]);
;                 const bf16x8 pa = __builtin_bit_cast(bf16x8, pw);
;                 __builtin_amdgcn_sched_barrier(0);
; #pragma unroll
;                 for (int dt = 0; dt < DV / 32; ++dt) o[dt] = __builtin_amdgcn_mfma_f32_32x32x16_bf16(pa, vc[dt], o[dt], 0, 0, 0);
;                 __builtin_amdgcn_sched_barrier(0x1 | 0x2 | 0x100);
;             }
;             l_run += rs;
;     ...
;         }
;         }
;         if (t + 1 < t_hi) AT_STORE(cur ^ 1);
.LBB0_963:
	v_exp_f32_e32 v50, v50
	v_exp_f32_e32 v51, v51
	v_exp_f32_e32 v52, v52
	v_exp_f32_e32 v53, v53
	v_add_u32_e32 v140, v140, v137
	v_add_f32_e32 v146, 0, v50
	v_exp_f32_e32 v54, v54
	v_add_u32_e32 v144, 0x9000, v140
	v_add_u32_e32 v145, 0xb000, v140
	v_add_f32_e32 v146, v51, v146
	v_exp_f32_e32 v55, v55
	ds_read2_b64 v[102:105], v144 offset0:16 offset1:18
	ds_read2_b64 v[140:143], v145 offset0:48 offset1:50
	v_add_f32_e32 v146, v52, v146
	v_exp_f32_e32 v56, v56
	v_exp_f32_e32 v57, v57
	v_add_f32_e32 v146, v53, v146
	v_add_f32_e32 v146, v54, v146
	v_add_f32_e32 v146, v55, v146
	v_add_f32_e32 v146, v56, v146
	v_cvt_pk_bf16_f32 v50, v50, v51
	v_cvt_pk_bf16_f32 v51, v52, v53
	v_cvt_pk_bf16_f32 v52, v54, v55
	v_cvt_pk_bf16_f32 v53, v56, v57
	v_exp_f32_e32 v58, v58
	v_exp_f32_e32 v59, v59
	s_waitcnt lgkmcnt(1)
	v_mfma_f32_32x32x16_bf16 v[18:33], v[50:53], v[102:105], v[18:33]
	v_exp_f32_e32 v60, v60
	v_add_f32_e32 v102, v57, v146
	v_exp_f32_e32 v61, v61
	v_add_f32_e32 v102, v58, v102
	v_exp_f32_e32 v62, v62
	v_add_f32_e32 v102, v59, v102
	v_exp_f32_e32 v63, v63
	s_waitcnt lgkmcnt(0)
	v_mfma_f32_32x32x16_bf16 v[2:17], v[50:53], v[140:143], v[2:17]
	ds_read2_b64 v[50:53], v144 offset0:20 offset1:22
	ds_read2_b64 v[54:57], v145 offset0:52 offset1:54
	v_add_f32_e32 v102, v60, v102
	v_exp_f32_e32 v64, v64
	v_exp_f32_e32 v65, v65
	v_add_f32_e32 v102, v61, v102
	v_add_f32_e32 v102, v62, v102
	v_add_f32_e32 v102, v63, v102
	v_add_f32_e32 v102, v64, v102
	v_cvt_pk_bf16_f32 v58, v58, v59
	v_cvt_pk_bf16_f32 v59, v60, v61
	v_cvt_pk_bf16_f32 v60, v62, v63
	v_cvt_pk_bf16_f32 v61, v64, v65
	v_exp_f32_e32 v34, v34
	v_exp_f32_e32 v35, v35
	s_waitcnt lgkmcnt(1)
	v_mfma_f32_32x32x16_bf16 v[18:33], v[58:61], v[50:53], v[18:33]
	v_exp_f32_e32 v36, v36
	v_exp_f32_e32 v37, v37
	v_exp_f32_e32 v38, v38
	v_exp_f32_e32 v39, v39
	v_exp_f32_e32 v40, v40
	v_exp_f32_e32 v41, v41
	s_waitcnt lgkmcnt(0)
	v_mfma_f32_32x32x16_bf16 v[2:17], v[58:61], v[54:57], v[2:17]
	v_add_f32_e32 v58, v65, v102
	v_add_f32_e32 v58, v34, v58
	ds_read2_b64 v[50:53], v144 offset0:24 offset1:26
	ds_read2_b64 v[54:57], v145 offset0:56 offset1:58
	v_add_f32_e32 v58, v35, v58
	v_add_f32_e32 v58, v36, v58
	v_add_f32_e32 v58, v37, v58
	v_add_f32_e32 v58, v38, v58
	v_add_f32_e32 v58, v39, v58
	v_add_f32_e32 v58, v40, v58
	v_cvt_pk_bf16_f32 v34, v34, v35
	v_cvt_pk_bf16_f32 v35, v36, v37
	v_cvt_pk_bf16_f32 v36, v38, v39
	v_cvt_pk_bf16_f32 v37, v40, v41
	v_exp_f32_e32 v42, v42
	v_exp_f32_e32 v43, v43
	s_waitcnt lgkmcnt(1)
	v_mfma_f32_32x32x16_bf16 v[18:33], v[34:37], v[50:53], v[18:33]
	v_exp_f32_e32 v44, v44
	v_add_f32_e32 v50, v41, v58
	v_exp_f32_e32 v45, v45
	v_add_f32_e32 v50, v42, v50
	v_exp_f32_e32 v46, v46
	v_add_f32_e32 v50, v43, v50
	v_exp_f32_e32 v47, v47
	s_waitcnt lgkmcnt(0)
	v_mfma_f32_32x32x16_bf16 v[2:17], v[34:37], v[54:57], v[2:17]
	ds_read2_b64 v[34:37], v144 offset0:28 offset1:30
	ds_read2_b64 v[38:41], v145 offset0:60 offset1:62
	v_add_f32_e32 v50, v44, v50
	v_exp_f32_e32 v48, v48
	v_exp_f32_e32 v49, v49
	v_add_f32_e32 v50, v45, v50
	v_add_f32_e32 v50, v46, v50
	v_add_f32_e32 v50, v47, v50
	v_add_f32_e32 v50, v48, v50
	v_cvt_pk_bf16_f32 v42, v42, v43
	v_cvt_pk_bf16_f32 v43, v44, v45
	v_cvt_pk_bf16_f32 v44, v46, v47
	v_cvt_pk_bf16_f32 v45, v48, v49
	s_waitcnt lgkmcnt(1)
	s_nop 0
	v_mfma_f32_32x32x16_bf16 v[18:33], v[42:45], v[34:37], v[18:33]
	v_add_f32_e32 v34, v49, v50
	v_add_f32_e32 v133, v133, v34
	v_cmp_lt_f32_e32 vcc, 0x43800000, v34
	s_waitcnt lgkmcnt(0)
	v_mfma_f32_32x32x16_bf16 v[2:17], v[42:45], v[38:41], v[2:17]
	s_cbranch_vccnz .Lrare_7
.Lback_7:
.LBB0_964:
	s_xor_b32 s72, s72, 1
	s_and_b64 vcc, exec, s[10:11]
	s_cbranch_vccz .LBB0_966
	s_mul_i32 s9, s72, 0x4800
	s_add_i32 s9, s9, 0
	v_add3_u32 v34, s9, v124, v125
	s_mul_i32 s10, s72, 0xfffffa00
	s_waitcnt vmcnt(4)
	ds_write_b128 v34, v[66:69]
	v_add3_u32 v34, s9, v126, v127
	s_add_i32 s9, s9, s10
	s_waitcnt vmcnt(3)
	ds_write_b128 v34, v[70:73]
	v_add_u32_e32 v34, s9, v128
	v_add3_u32 v34, v34, v129, s92
	s_waitcnt vmcnt(2)
	ds_write2_b64 v34, v[74:75], v[76:77] offset1:1
	v_add_u32_e32 v34, s9, v130
	v_add3_u32 v34, v34, v131, s92
	s_waitcnt vmcnt(1)
	ds_write2_b64 v34, v[78:79], v[80:81] offset1:1
